# v25 + attention store_o (3 mixers): the 64 half-masked global_store_dword per wave staged through the dead K/V LDS region and written as 8 row-contiguous global_store_dwordx4
# speedup vs baseline: 1.0036x; 1.0013x over previous
.LBB0_340:
	v_lshlrev_b32_e32 v4, 2, v185
	global_load_dword v2, v4, s[6:7]
	global_load_dword v3, v4, s[6:7] offset:128
	global_load_dword v6, v4, s[6:7] offset:256
	global_load_dword v7, v4, s[6:7] offset:384
	v_mul_f32_e32 v5, v116, v116
	v_mul_f32_e32 v8, v148, v148
	v_mul_f32_e32 v9, v117, v117
	v_mul_f32_e32 v10, v149, v149
	v_fmac_f32_e32 v5, v68, v68
	s_waitcnt vmcnt(6)
	v_fmac_f32_e32 v8, v132, v132
	v_fmac_f32_e32 v9, v69, v69
	v_fmac_f32_e32 v10, v133, v133
	v_add_f32_e32 v4, v5, v8
	v_add_f32_e32 v5, v9, v10
	v_mul_f32_e32 v21, v123, v123
	v_add_f32_dpp v4, v4, v4 quad_perm:[1,0,3,2] row_mask:0xf bank_mask:0xf bound_ctrl:1
	v_add_f32_dpp v5, v5, v5 quad_perm:[1,0,3,2] row_mask:0xf bank_mask:0xf bound_ctrl:1
	v_mul_f32_e32 v22, v155, v155
	v_add_f32_dpp v4, v4, v4 quad_perm:[2,3,0,1] row_mask:0xf bank_mask:0xf bound_ctrl:1
	v_add_f32_dpp v5, v5, v5 quad_perm:[2,3,0,1] row_mask:0xf bank_mask:0xf bound_ctrl:1
	v_fmac_f32_e32 v21, v75, v75
	v_add_f32_dpp v4, v4, v4 row_half_mirror row_mask:0xf bank_mask:0xf bound_ctrl:1
	v_add_f32_dpp v5, v5, v5 row_half_mirror row_mask:0xf bank_mask:0xf bound_ctrl:1
	s_waitcnt vmcnt(5)
	v_fmac_f32_e32 v22, v139, v139
	v_add_f32_dpp v4, v4, v4 row_mirror row_mask:0xf bank_mask:0xf bound_ctrl:1
	v_add_f32_dpp v40, v5, v5 row_mirror row_mask:0xf bank_mask:0xf bound_ctrl:1
	ds_swizzle_b32 v5, v4 offset:swizzle(SWAP,16)
	v_mul_f32_e32 v11, v118, v118
	v_mul_f32_e32 v12, v150, v150
	v_mul_f32_e32 v19, v122, v122
	v_mul_f32_e32 v20, v154, v154
	s_waitcnt lgkmcnt(0)
	v_add_f32_e32 v4, v4, v5
	v_fmamk_f32 v4, v4, 0x3c000000, v214
	v_rsq_f32_e32 v42, v4
	v_mul_f32_e32 v5, v156, v156
	s_waitcnt vmcnt(4)
	v_fmac_f32_e32 v5, v140, v140
	v_fmac_f32_e32 v11, v70, v70
	v_fmac_f32_e32 v12, v134, v134
	v_fmac_f32_e32 v19, v74, v74
	v_fmac_f32_e32 v20, v138, v138
	v_add_f32_e32 v8, v11, v12
	v_add_f32_e32 v12, v19, v20
	v_mul_f32_e32 v17, v121, v121
	v_mul_f32_e32 v18, v153, v153
	v_fmac_f32_e32 v17, v73, v73
	v_fmac_f32_e32 v18, v137, v137
	v_add_f32_e32 v11, v17, v18
	v_mul_f32_e32 v15, v120, v120
	v_mul_f32_e32 v16, v152, v152
	v_fmac_f32_e32 v15, v72, v72
	v_fmac_f32_e32 v16, v136, v136
	v_add_f32_e32 v10, v15, v16
	v_mul_f32_e32 v13, v119, v119
	v_mul_f32_e32 v14, v151, v151
	v_fmac_f32_e32 v13, v71, v71
	v_fmac_f32_e32 v14, v135, v135
	v_add_f32_e32 v9, v13, v14
	v_add_f32_dpp v12, v12, v12 quad_perm:[1,0,3,2] row_mask:0xf bank_mask:0xf bound_ctrl:1
	s_ashr_i32 s9, s53, 31
	s_add_u32 s8, s54, s53
	v_add_f32_dpp v12, v12, v12 quad_perm:[2,3,0,1] row_mask:0xf bank_mask:0xf bound_ctrl:1
	s_addc_u32 s9, s55, s9
	v_add_f32_dpp v8, v8, v8 quad_perm:[1,0,3,2] row_mask:0xf bank_mask:0xf bound_ctrl:1
	v_add_f32_dpp v12, v12, v12 row_half_mirror row_mask:0xf bank_mask:0xf bound_ctrl:1
	v_add_f32_dpp v9, v9, v9 quad_perm:[1,0,3,2] row_mask:0xf bank_mask:0xf bound_ctrl:1
	v_add_f32_dpp v10, v10, v10 quad_perm:[1,0,3,2] row_mask:0xf bank_mask:0xf bound_ctrl:1
	v_add_f32_dpp v28, v12, v12 row_mirror row_mask:0xf bank_mask:0xf bound_ctrl:1
	v_add_f32_dpp v11, v11, v11 quad_perm:[1,0,3,2] row_mask:0xf bank_mask:0xf bound_ctrl:1
	s_lshl_b64 s[8:9], s[8:9], 12
	v_readlane_b32 s10, v252, 59
	v_add_f32_dpp v8, v8, v8 quad_perm:[2,3,0,1] row_mask:0xf bank_mask:0xf bound_ctrl:1
	v_add_f32_dpp v9, v9, v9 quad_perm:[2,3,0,1] row_mask:0xf bank_mask:0xf bound_ctrl:1
	v_add_f32_dpp v10, v10, v10 quad_perm:[2,3,0,1] row_mask:0xf bank_mask:0xf bound_ctrl:1
	v_add_f32_dpp v11, v11, v11 quad_perm:[2,3,0,1] row_mask:0xf bank_mask:0xf bound_ctrl:1
	s_add_u32 s10, s10, s8
	v_readlane_b32 s8, v252, 60
	v_add_f32_dpp v8, v8, v8 row_half_mirror row_mask:0xf bank_mask:0xf bound_ctrl:1
	v_add_f32_dpp v9, v9, v9 row_half_mirror row_mask:0xf bank_mask:0xf bound_ctrl:1
	v_add_f32_dpp v10, v10, v10 row_half_mirror row_mask:0xf bank_mask:0xf bound_ctrl:1
	v_add_f32_dpp v11, v11, v11 row_half_mirror row_mask:0xf bank_mask:0xf bound_ctrl:1
	s_addc_u32 s11, s8, s9
	s_ashr_i32 s53, s52, 31
	s_waitcnt vmcnt(2)
	v_pk_mul_f32 v[2:3], v[186:187], v[2:3]
	v_add_f32_dpp v38, v8, v8 row_mirror row_mask:0xf bank_mask:0xf bound_ctrl:1
	v_mul_f32_e32 v4, v2, v42
	v_mul_f32_e32 v43, v68, v4
	v_add_f32_e32 v4, v21, v22
	v_add_f32_dpp v36, v9, v9 row_mirror row_mask:0xf bank_mask:0xf bound_ctrl:1
	v_add_f32_dpp v32, v10, v10 row_mirror row_mask:0xf bank_mask:0xf bound_ctrl:1
	v_add_f32_dpp v4, v4, v4 quad_perm:[1,0,3,2] row_mask:0xf bank_mask:0xf bound_ctrl:1
	v_add_f32_dpp v30, v11, v11 row_mirror row_mask:0xf bank_mask:0xf bound_ctrl:1
	s_lshl_b64 s[8:9], s[52:53], 1
	v_add_f32_dpp v4, v4, v4 quad_perm:[2,3,0,1] row_mask:0xf bank_mask:0xf bound_ctrl:1
	ds_swizzle_b32 v41, v40 offset:swizzle(SWAP,16)
	ds_swizzle_b32 v39, v38 offset:swizzle(SWAP,16)
	v_add_f32_dpp v4, v4, v4 row_half_mirror row_mask:0xf bank_mask:0xf bound_ctrl:1
	ds_swizzle_b32 v37, v36 offset:swizzle(SWAP,16)
	ds_swizzle_b32 v33, v32 offset:swizzle(SWAP,16)
	v_add_f32_dpp v26, v4, v4 row_mirror row_mask:0xf bank_mask:0xf bound_ctrl:1
	v_mul_f32_e32 v4, v124, v124
	v_fmac_f32_e32 v4, v76, v76
	v_add_f32_e32 v4, v4, v5
	v_mul_f32_e32 v5, v157, v157
	v_fmac_f32_e32 v5, v141, v141
	v_add_f32_dpp v4, v4, v4 quad_perm:[1,0,3,2] row_mask:0xf bank_mask:0xf bound_ctrl:1
	ds_swizzle_b32 v31, v30 offset:swizzle(SWAP,16)
	ds_swizzle_b32 v29, v28 offset:swizzle(SWAP,16)
	v_add_f32_dpp v4, v4, v4 quad_perm:[2,3,0,1] row_mask:0xf bank_mask:0xf bound_ctrl:1
	ds_swizzle_b32 v27, v26 offset:swizzle(SWAP,16)
	s_add_u32 s8, s10, s8
	v_add_f32_dpp v4, v4, v4 row_half_mirror row_mask:0xf bank_mask:0xf bound_ctrl:1
	s_addc_u32 s9, s11, s9
	v_lshlrev_b32_e32 v34, 1, v185
	v_add_f32_dpp v24, v4, v4 row_mirror row_mask:0xf bank_mask:0xf bound_ctrl:1
	v_mul_f32_e32 v4, v125, v125
	v_fmac_f32_e32 v4, v77, v77
	v_add_f32_e32 v4, v4, v5
	v_mul_f32_e32 v5, v158, v158
	v_fmac_f32_e32 v5, v142, v142
	v_add_f32_dpp v4, v4, v4 quad_perm:[1,0,3,2] row_mask:0xf bank_mask:0xf bound_ctrl:1
	ds_swizzle_b32 v25, v24 offset:swizzle(SWAP,16)
	v_lshl_add_u64 v[8:9], s[8:9], 0, v[34:35]
	v_add_f32_dpp v4, v4, v4 quad_perm:[2,3,0,1] row_mask:0xf bank_mask:0xf bound_ctrl:1
	v_and_b32_e32 v1, 1, v1
	s_mov_b64 s[8:9], 0x600
	v_add_f32_dpp v4, v4, v4 row_half_mirror row_mask:0xf bank_mask:0xf bound_ctrl:1
	v_cmp_eq_u32_e64 s[38:39], 0, v1
	v_mov_b32_dpp v1, v43 quad_perm:[1,0,3,2] row_mask:0xf bank_mask:0xf bound_ctrl:1
	v_add_f32_dpp v22, v4, v4 row_mirror row_mask:0xf bank_mask:0xf bound_ctrl:1
	v_mul_f32_e32 v4, v126, v126
	v_fmac_f32_e32 v4, v78, v78
	v_add_f32_e32 v4, v4, v5
	v_mul_f32_e32 v5, v159, v159
	v_fmac_f32_e32 v5, v143, v143
	v_add_f32_dpp v4, v4, v4 quad_perm:[1,0,3,2] row_mask:0xf bank_mask:0xf bound_ctrl:1
	ds_swizzle_b32 v23, v22 offset:swizzle(SWAP,16)
	s_nop 0
	v_add_f32_dpp v4, v4, v4 quad_perm:[2,3,0,1] row_mask:0xf bank_mask:0xf bound_ctrl:1
	s_nop 1
	v_add_f32_dpp v4, v4, v4 row_half_mirror row_mask:0xf bank_mask:0xf bound_ctrl:1
	s_nop 1
	v_add_f32_dpp v20, v4, v4 row_mirror row_mask:0xf bank_mask:0xf bound_ctrl:1
	v_mul_f32_e32 v4, v127, v127
	v_fmac_f32_e32 v4, v79, v79
	v_add_f32_e32 v4, v4, v5
	v_mul_f32_e32 v5, v160, v160
	v_fmac_f32_e32 v5, v144, v144
	v_add_f32_dpp v4, v4, v4 quad_perm:[1,0,3,2] row_mask:0xf bank_mask:0xf bound_ctrl:1
	ds_swizzle_b32 v21, v20 offset:swizzle(SWAP,16)
	s_nop 0
	v_add_f32_dpp v4, v4, v4 quad_perm:[2,3,0,1] row_mask:0xf bank_mask:0xf bound_ctrl:1
	s_nop 1
	v_add_f32_dpp v4, v4, v4 row_half_mirror row_mask:0xf bank_mask:0xf bound_ctrl:1
	s_nop 1
	v_add_f32_dpp v18, v4, v4 row_mirror row_mask:0xf bank_mask:0xf bound_ctrl:1
	v_mul_f32_e32 v4, v128, v128
	v_fmac_f32_e32 v4, v80, v80
	v_add_f32_e32 v4, v4, v5
	v_mul_f32_e32 v5, v161, v161
	v_fmac_f32_e32 v5, v145, v145
	v_add_f32_dpp v4, v4, v4 quad_perm:[1,0,3,2] row_mask:0xf bank_mask:0xf bound_ctrl:1
	ds_swizzle_b32 v19, v18 offset:swizzle(SWAP,16)
	s_nop 0
	v_add_f32_dpp v4, v4, v4 quad_perm:[2,3,0,1] row_mask:0xf bank_mask:0xf bound_ctrl:1
	s_nop 1
	v_add_f32_dpp v4, v4, v4 row_half_mirror row_mask:0xf bank_mask:0xf bound_ctrl:1
	s_nop 1
	v_add_f32_dpp v16, v4, v4 row_mirror row_mask:0xf bank_mask:0xf bound_ctrl:1
	v_mul_f32_e32 v4, v129, v129
	v_fmac_f32_e32 v4, v81, v81
	v_add_f32_e32 v4, v4, v5
	v_mul_f32_e32 v5, v162, v162
	v_fmac_f32_e32 v5, v146, v146
	v_add_f32_dpp v4, v4, v4 quad_perm:[1,0,3,2] row_mask:0xf bank_mask:0xf bound_ctrl:1
	ds_swizzle_b32 v17, v16 offset:swizzle(SWAP,16)
	s_nop 0
	v_add_f32_dpp v4, v4, v4 quad_perm:[2,3,0,1] row_mask:0xf bank_mask:0xf bound_ctrl:1
	s_nop 1
	v_add_f32_dpp v4, v4, v4 row_half_mirror row_mask:0xf bank_mask:0xf bound_ctrl:1
	s_nop 1
	v_add_f32_dpp v14, v4, v4 row_mirror row_mask:0xf bank_mask:0xf bound_ctrl:1
	v_mul_f32_e32 v4, v130, v130
	v_fmac_f32_e32 v4, v82, v82
	v_add_f32_e32 v4, v4, v5
	v_mul_f32_e32 v5, v163, v163
	v_fmac_f32_e32 v5, v147, v147
	v_add_f32_dpp v4, v4, v4 quad_perm:[1,0,3,2] row_mask:0xf bank_mask:0xf bound_ctrl:1
	ds_swizzle_b32 v15, v14 offset:swizzle(SWAP,16)
	s_nop 0
	v_add_f32_dpp v4, v4, v4 quad_perm:[2,3,0,1] row_mask:0xf bank_mask:0xf bound_ctrl:1
	s_nop 1
	v_add_f32_dpp v4, v4, v4 row_half_mirror row_mask:0xf bank_mask:0xf bound_ctrl:1
	s_nop 1
	v_add_f32_dpp v12, v4, v4 row_mirror row_mask:0xf bank_mask:0xf bound_ctrl:1
	v_mul_f32_e32 v4, v131, v131
	v_fmac_f32_e32 v4, v83, v83
	v_add_f32_e32 v4, v4, v5
	ds_swizzle_b32 v13, v12 offset:swizzle(SWAP,16)
	v_mov_b32_e32 v5, v35
	v_add_f32_dpp v4, v4, v4 quad_perm:[1,0,3,2] row_mask:0xf bank_mask:0xf bound_ctrl:1
	s_nop 1
	v_add_f32_dpp v4, v4, v4 quad_perm:[2,3,0,1] row_mask:0xf bank_mask:0xf bound_ctrl:1
	s_nop 1
	v_add_f32_dpp v4, v4, v4 row_half_mirror row_mask:0xf bank_mask:0xf bound_ctrl:1
	s_nop 1
	v_add_f32_dpp v10, v4, v4 row_mirror row_mask:0xf bank_mask:0xf bound_ctrl:1
	ds_swizzle_b32 v11, v10 offset:swizzle(SWAP,16)
	v_lshlrev_b32_e32 v4, 14, v189
	v_lshl_add_u64 v[8:9], v[8:9], 0, v[4:5]
	v_lshl_add_u64 v[4:5], v[8:9], 0, s[8:9]
	v_and_b32_e32 v218, 0x1c0, v0
	v_lshlrev_b32_e32 v218, 7, v218
	v_and_b32_e32 v219, 32, v0
	v_lshl_add_u32 v218, v219, 5, v218
	v_and_b32_e32 v219, 31, v0
	v_lshl_add_u32 v218, v219, 1, v218
	s_and_saveexec_b64 s[8:9], s[38:39]
	v_cvt_pk_bf16_f32 v1, v43, v1
	ds_write_b32 v218, v1 offset:0
.LBB0_342:
	s_or_b64 exec, exec, s[8:9]
	v_mul_f32_e32 v1, v3, v42
	v_mov_b32_e32 v185, v184
	v_mul_f32_e32 v1, v116, v1
	s_waitcnt vmcnt(0)
	v_pk_mul_f32 v[6:7], v[184:185], v[6:7]
	v_mov_b32_dpp v34, v1 quad_perm:[1,0,3,2] row_mask:0xf bank_mask:0xf bound_ctrl:1
	s_and_saveexec_b64 s[8:9], s[38:39]
	s_movk_i32 s83, 0x6000
	s_mov_b64 s[84:85], 0x6000
	v_readlane_b32 s86, v255, 46
	v_cvt_pk_bf16_f32 v1, v1, v34
	ds_write_b32 v218, v1 offset:64
.LBB0_344:
	s_or_b64 exec, exec, s[8:9]
	v_mul_f32_e32 v1, v6, v42
	v_mul_f32_e32 v1, v132, v1
	s_nop 1
	v_mov_b32_dpp v34, v1 quad_perm:[1,0,3,2] row_mask:0xf bank_mask:0xf bound_ctrl:1
	s_and_saveexec_b64 s[8:9], s[38:39]
	v_cvt_pk_bf16_f32 v1, v1, v34
	ds_write_b32 v218, v1 offset:128
.LBB0_346:
	s_or_b64 exec, exec, s[8:9]
	v_mul_f32_e32 v1, v7, v42
	v_mul_f32_e32 v1, v148, v1
	s_nop 1
	v_mov_b32_dpp v34, v1 quad_perm:[1,0,3,2] row_mask:0xf bank_mask:0xf bound_ctrl:1
	s_and_saveexec_b64 s[8:9], s[38:39]
	v_cvt_pk_bf16_f32 v1, v1, v34
	ds_write_b32 v218, v1 offset:192
.LBB0_348:
	s_or_b64 exec, exec, s[8:9]
	s_waitcnt lgkmcnt(14)
	v_add_f32_e32 v1, v40, v41
	v_fmamk_f32 v1, v1, 0x3c000000, v214
	v_rsq_f32_e32 v1, v1
	s_nop 0
	v_mul_f32_e32 v8, v2, v1
	v_mul_f32_e32 v8, v69, v8
	s_nop 1
	v_mov_b32_dpp v9, v8 quad_perm:[1,0,3,2] row_mask:0xf bank_mask:0xf bound_ctrl:1
	s_and_saveexec_b64 s[8:9], s[38:39]
	v_cvt_pk_bf16_f32 v34, v8, v9
	ds_write_b32 v218, v34 offset:256
.LBB0_350:
	s_or_b64 exec, exec, s[8:9]
	v_mul_f32_e32 v8, v3, v1
	v_mul_f32_e32 v8, v117, v8
	s_nop 1
	v_mov_b32_dpp v9, v8 quad_perm:[1,0,3,2] row_mask:0xf bank_mask:0xf bound_ctrl:1
	s_and_saveexec_b64 s[8:9], s[38:39]
	v_cvt_pk_bf16_f32 v34, v8, v9
	ds_write_b32 v218, v34 offset:320
.LBB0_352:
	s_or_b64 exec, exec, s[8:9]
	v_mul_f32_e32 v8, v6, v1
	v_mul_f32_e32 v8, v133, v8
	s_nop 1
	v_mov_b32_dpp v9, v8 quad_perm:[1,0,3,2] row_mask:0xf bank_mask:0xf bound_ctrl:1
	s_and_saveexec_b64 s[8:9], s[38:39]
	v_cvt_pk_bf16_f32 v34, v8, v9
	ds_write_b32 v218, v34 offset:384
.LBB0_354:
	s_or_b64 exec, exec, s[8:9]
	v_mul_f32_e32 v1, v7, v1
	v_mul_f32_e32 v1, v149, v1
	s_nop 1
	v_mov_b32_dpp v8, v1 quad_perm:[1,0,3,2] row_mask:0xf bank_mask:0xf bound_ctrl:1
	s_and_saveexec_b64 s[8:9], s[38:39]
	v_cvt_pk_bf16_f32 v1, v1, v8
	ds_write_b32 v218, v1 offset:448
.LBB0_356:
	s_or_b64 exec, exec, s[8:9]
	s_waitcnt lgkmcnt(13)
	v_add_f32_e32 v1, v38, v39
	v_fmamk_f32 v1, v1, 0x3c000000, v214
	v_rsq_f32_e32 v1, v1
	s_nop 0
	v_mul_f32_e32 v8, v2, v1
	v_mul_f32_e32 v8, v70, v8
	s_nop 1
	v_mov_b32_dpp v9, v8 quad_perm:[1,0,3,2] row_mask:0xf bank_mask:0xf bound_ctrl:1
	s_and_saveexec_b64 s[8:9], s[38:39]
	v_cvt_pk_bf16_f32 v34, v8, v9
	ds_write_b32 v218, v34 offset:512
.LBB0_358:
	s_or_b64 exec, exec, s[8:9]
	v_mul_f32_e32 v8, v3, v1
	v_mul_f32_e32 v8, v118, v8
	s_nop 1
	v_mov_b32_dpp v9, v8 quad_perm:[1,0,3,2] row_mask:0xf bank_mask:0xf bound_ctrl:1
	s_and_saveexec_b64 s[8:9], s[38:39]
	v_cvt_pk_bf16_f32 v34, v8, v9
	ds_write_b32 v218, v34 offset:576
.LBB0_360:
	s_or_b64 exec, exec, s[8:9]
	v_mul_f32_e32 v8, v6, v1
	v_mul_f32_e32 v8, v134, v8
	s_nop 1
	v_mov_b32_dpp v9, v8 quad_perm:[1,0,3,2] row_mask:0xf bank_mask:0xf bound_ctrl:1
	s_and_saveexec_b64 s[8:9], s[38:39]
	v_cvt_pk_bf16_f32 v34, v8, v9
	ds_write_b32 v218, v34 offset:640
.LBB0_362:
	s_or_b64 exec, exec, s[8:9]
	v_mul_f32_e32 v1, v7, v1
	v_mul_f32_e32 v1, v150, v1
	s_nop 1
	v_mov_b32_dpp v8, v1 quad_perm:[1,0,3,2] row_mask:0xf bank_mask:0xf bound_ctrl:1
	s_and_saveexec_b64 s[8:9], s[38:39]
	v_cvt_pk_bf16_f32 v1, v1, v8
	ds_write_b32 v218, v1 offset:704
.LBB0_364:
	s_or_b64 exec, exec, s[8:9]
	s_waitcnt lgkmcnt(12)
	v_add_f32_e32 v1, v36, v37
	v_fmamk_f32 v1, v1, 0x3c000000, v214
	v_rsq_f32_e32 v1, v1
	s_nop 0
	v_mul_f32_e32 v8, v2, v1
	v_mul_f32_e32 v8, v71, v8
	s_nop 1
	v_mov_b32_dpp v9, v8 quad_perm:[1,0,3,2] row_mask:0xf bank_mask:0xf bound_ctrl:1
	s_and_saveexec_b64 s[8:9], s[38:39]
	v_cvt_pk_bf16_f32 v34, v8, v9
	ds_write_b32 v218, v34 offset:768
.LBB0_366:
	s_or_b64 exec, exec, s[8:9]
	v_mul_f32_e32 v8, v3, v1
	v_mul_f32_e32 v8, v119, v8
	s_nop 1
	v_mov_b32_dpp v9, v8 quad_perm:[1,0,3,2] row_mask:0xf bank_mask:0xf bound_ctrl:1
	s_and_saveexec_b64 s[8:9], s[38:39]
	v_cvt_pk_bf16_f32 v34, v8, v9
	ds_write_b32 v218, v34 offset:832
.LBB0_368:
	s_or_b64 exec, exec, s[8:9]
	v_mul_f32_e32 v8, v6, v1
	v_mul_f32_e32 v8, v135, v8
	s_nop 1
	v_mov_b32_dpp v9, v8 quad_perm:[1,0,3,2] row_mask:0xf bank_mask:0xf bound_ctrl:1
	s_and_saveexec_b64 s[8:9], s[38:39]
	v_cvt_pk_bf16_f32 v34, v8, v9
	ds_write_b32 v218, v34 offset:896
.LBB0_370:
	s_or_b64 exec, exec, s[8:9]
	v_mul_f32_e32 v1, v7, v1
	v_mul_f32_e32 v1, v151, v1
	s_nop 1
	v_mov_b32_dpp v8, v1 quad_perm:[1,0,3,2] row_mask:0xf bank_mask:0xf bound_ctrl:1
	s_and_saveexec_b64 s[8:9], s[38:39]
	v_cvt_pk_bf16_f32 v1, v1, v8
	ds_write_b32 v218, v1 offset:960
.LBB0_372:
	s_or_b64 exec, exec, s[8:9]
	s_waitcnt lgkmcnt(11)
	v_add_f32_e32 v1, v32, v33
	v_fmamk_f32 v1, v1, 0x3c000000, v214
	v_rsq_f32_e32 v1, v1
	s_nop 0
	v_mul_f32_e32 v8, v2, v1
	v_mul_f32_e32 v8, v72, v8
	s_nop 1
	v_mov_b32_dpp v9, v8 quad_perm:[1,0,3,2] row_mask:0xf bank_mask:0xf bound_ctrl:1
	s_and_saveexec_b64 s[8:9], s[38:39]
	v_cvt_pk_bf16_f32 v32, v8, v9
	ds_write_b32 v218, v32 offset:2048
.LBB0_374:
	s_or_b64 exec, exec, s[8:9]
	v_mul_f32_e32 v8, v3, v1
	v_mul_f32_e32 v8, v120, v8
	s_nop 1
	v_mov_b32_dpp v9, v8 quad_perm:[1,0,3,2] row_mask:0xf bank_mask:0xf bound_ctrl:1
	s_and_saveexec_b64 s[8:9], s[38:39]
	v_cvt_pk_bf16_f32 v32, v8, v9
	ds_write_b32 v218, v32 offset:2112
.LBB0_376:
	s_or_b64 exec, exec, s[8:9]
	v_mul_f32_e32 v8, v6, v1
	v_mul_f32_e32 v8, v136, v8
	s_nop 1
	v_mov_b32_dpp v9, v8 quad_perm:[1,0,3,2] row_mask:0xf bank_mask:0xf bound_ctrl:1
	s_and_saveexec_b64 s[8:9], s[38:39]
	v_cvt_pk_bf16_f32 v32, v8, v9
	ds_write_b32 v218, v32 offset:2176
.LBB0_378:
	s_or_b64 exec, exec, s[8:9]
	v_mul_f32_e32 v1, v7, v1
	v_mul_f32_e32 v1, v152, v1
	s_nop 1
	v_mov_b32_dpp v8, v1 quad_perm:[1,0,3,2] row_mask:0xf bank_mask:0xf bound_ctrl:1
	s_and_saveexec_b64 s[8:9], s[38:39]
	v_cvt_pk_bf16_f32 v1, v1, v8
	ds_write_b32 v218, v1 offset:2240
.LBB0_380:
	s_or_b64 exec, exec, s[8:9]
	s_waitcnt lgkmcnt(10)
	v_add_f32_e32 v1, v30, v31
	v_fmamk_f32 v1, v1, 0x3c000000, v214
	v_rsq_f32_e32 v1, v1
	s_nop 0
	v_mul_f32_e32 v8, v2, v1
	v_mul_f32_e32 v8, v73, v8
	s_nop 1
	v_mov_b32_dpp v9, v8 quad_perm:[1,0,3,2] row_mask:0xf bank_mask:0xf bound_ctrl:1
	s_and_saveexec_b64 s[8:9], s[38:39]
	v_cvt_pk_bf16_f32 v30, v8, v9
	ds_write_b32 v218, v30 offset:2304
.LBB0_382:
	s_or_b64 exec, exec, s[8:9]
	v_mul_f32_e32 v8, v3, v1
	v_mul_f32_e32 v8, v121, v8
	s_nop 1
	v_mov_b32_dpp v9, v8 quad_perm:[1,0,3,2] row_mask:0xf bank_mask:0xf bound_ctrl:1
	s_and_saveexec_b64 s[8:9], s[38:39]
	v_cvt_pk_bf16_f32 v30, v8, v9
	ds_write_b32 v218, v30 offset:2368
.LBB0_384:
	s_or_b64 exec, exec, s[8:9]
	v_mul_f32_e32 v8, v6, v1
	v_mul_f32_e32 v8, v137, v8
	s_nop 1
	v_mov_b32_dpp v9, v8 quad_perm:[1,0,3,2] row_mask:0xf bank_mask:0xf bound_ctrl:1
	s_and_saveexec_b64 s[8:9], s[38:39]
	v_cvt_pk_bf16_f32 v30, v8, v9
	ds_write_b32 v218, v30 offset:2432
.LBB0_386:
	s_or_b64 exec, exec, s[8:9]
	v_mul_f32_e32 v1, v7, v1
	v_mul_f32_e32 v1, v153, v1
	s_nop 1
	v_mov_b32_dpp v8, v1 quad_perm:[1,0,3,2] row_mask:0xf bank_mask:0xf bound_ctrl:1
	s_and_saveexec_b64 s[8:9], s[38:39]
	v_cvt_pk_bf16_f32 v1, v1, v8
	ds_write_b32 v218, v1 offset:2496
.LBB0_388:
	s_or_b64 exec, exec, s[8:9]
	s_waitcnt lgkmcnt(9)
	v_add_f32_e32 v1, v28, v29
	v_fmamk_f32 v1, v1, 0x3c000000, v214
	v_rsq_f32_e32 v1, v1
	s_nop 0
	v_mul_f32_e32 v8, v2, v1
	v_mul_f32_e32 v8, v74, v8
	s_nop 1
	v_mov_b32_dpp v9, v8 quad_perm:[1,0,3,2] row_mask:0xf bank_mask:0xf bound_ctrl:1
	s_and_saveexec_b64 s[8:9], s[38:39]
	v_cvt_pk_bf16_f32 v28, v8, v9
	ds_write_b32 v218, v28 offset:2560
.LBB0_390:
	s_or_b64 exec, exec, s[8:9]
	v_mul_f32_e32 v8, v3, v1
	v_mul_f32_e32 v8, v122, v8
	s_nop 1
	v_mov_b32_dpp v9, v8 quad_perm:[1,0,3,2] row_mask:0xf bank_mask:0xf bound_ctrl:1
	s_and_saveexec_b64 s[8:9], s[38:39]
	v_cvt_pk_bf16_f32 v28, v8, v9
	ds_write_b32 v218, v28 offset:2624
.LBB0_392:
	s_or_b64 exec, exec, s[8:9]
	v_mul_f32_e32 v8, v6, v1
	v_mul_f32_e32 v8, v138, v8
	s_nop 1
	v_mov_b32_dpp v9, v8 quad_perm:[1,0,3,2] row_mask:0xf bank_mask:0xf bound_ctrl:1
	s_and_saveexec_b64 s[8:9], s[38:39]
	v_cvt_pk_bf16_f32 v28, v8, v9
	ds_write_b32 v218, v28 offset:2688
.LBB0_394:
	s_or_b64 exec, exec, s[8:9]
	v_mul_f32_e32 v1, v7, v1
	v_mul_f32_e32 v1, v154, v1
	s_nop 1
	v_mov_b32_dpp v8, v1 quad_perm:[1,0,3,2] row_mask:0xf bank_mask:0xf bound_ctrl:1
	s_and_saveexec_b64 s[8:9], s[38:39]
	v_cvt_pk_bf16_f32 v1, v1, v8
	ds_write_b32 v218, v1 offset:2752
.LBB0_396:
	s_or_b64 exec, exec, s[8:9]
	s_waitcnt lgkmcnt(8)
	v_add_f32_e32 v1, v26, v27
	v_fmamk_f32 v1, v1, 0x3c000000, v214
	v_rsq_f32_e32 v1, v1
	s_nop 0
	v_mul_f32_e32 v8, v2, v1
	v_mul_f32_e32 v8, v75, v8
	s_nop 1
	v_mov_b32_dpp v9, v8 quad_perm:[1,0,3,2] row_mask:0xf bank_mask:0xf bound_ctrl:1
	s_and_saveexec_b64 s[8:9], s[38:39]
	v_cvt_pk_bf16_f32 v26, v8, v9
	ds_write_b32 v218, v26 offset:2816
.LBB0_398:
	s_or_b64 exec, exec, s[8:9]
	v_mul_f32_e32 v8, v3, v1
	v_mul_f32_e32 v8, v123, v8
	s_nop 1
	v_mov_b32_dpp v9, v8 quad_perm:[1,0,3,2] row_mask:0xf bank_mask:0xf bound_ctrl:1
	s_and_saveexec_b64 s[8:9], s[38:39]
	v_cvt_pk_bf16_f32 v26, v8, v9
	ds_write_b32 v218, v26 offset:2880
.LBB0_400:
	s_or_b64 exec, exec, s[8:9]
	v_mul_f32_e32 v8, v6, v1
	v_mul_f32_e32 v8, v139, v8
	s_nop 1
	v_mov_b32_dpp v9, v8 quad_perm:[1,0,3,2] row_mask:0xf bank_mask:0xf bound_ctrl:1
	s_and_saveexec_b64 s[8:9], s[38:39]
	v_cvt_pk_bf16_f32 v26, v8, v9
	ds_write_b32 v218, v26 offset:2944
.LBB0_402:
	s_or_b64 exec, exec, s[8:9]
	v_mul_f32_e32 v1, v7, v1
	v_mul_f32_e32 v1, v155, v1
	s_nop 1
	v_mov_b32_dpp v8, v1 quad_perm:[1,0,3,2] row_mask:0xf bank_mask:0xf bound_ctrl:1
	s_and_saveexec_b64 s[8:9], s[38:39]
	v_cvt_pk_bf16_f32 v1, v1, v8
	ds_write_b32 v218, v1 offset:3008
.LBB0_404:
	s_or_b64 exec, exec, s[8:9]
	s_waitcnt lgkmcnt(7)
	v_add_f32_e32 v1, v24, v25
	v_fmamk_f32 v1, v1, 0x3c000000, v214
	v_rsq_f32_e32 v1, v1
	s_nop 0
	v_mul_f32_e32 v8, v2, v1
	v_mul_f32_e32 v8, v76, v8
	s_nop 1
	v_mov_b32_dpp v9, v8 quad_perm:[1,0,3,2] row_mask:0xf bank_mask:0xf bound_ctrl:1
	s_and_saveexec_b64 s[8:9], s[38:39]
	v_cvt_pk_bf16_f32 v24, v8, v9
	ds_write_b32 v218, v24 offset:4096
.LBB0_406:
	s_or_b64 exec, exec, s[8:9]
	v_mul_f32_e32 v8, v3, v1
	v_mul_f32_e32 v8, v124, v8
	s_nop 1
	v_mov_b32_dpp v9, v8 quad_perm:[1,0,3,2] row_mask:0xf bank_mask:0xf bound_ctrl:1
	s_and_saveexec_b64 s[8:9], s[38:39]
	v_cvt_pk_bf16_f32 v24, v8, v9
	ds_write_b32 v218, v24 offset:4160
.LBB0_408:
	s_or_b64 exec, exec, s[8:9]
	v_mul_f32_e32 v8, v6, v1
	v_mul_f32_e32 v8, v140, v8
	s_nop 1
	v_mov_b32_dpp v9, v8 quad_perm:[1,0,3,2] row_mask:0xf bank_mask:0xf bound_ctrl:1
	s_and_saveexec_b64 s[8:9], s[38:39]
	v_cvt_pk_bf16_f32 v24, v8, v9
	ds_write_b32 v218, v24 offset:4224
.LBB0_410:
	s_or_b64 exec, exec, s[8:9]
	v_mul_f32_e32 v1, v7, v1
	v_mul_f32_e32 v1, v156, v1
	s_nop 1
	v_mov_b32_dpp v8, v1 quad_perm:[1,0,3,2] row_mask:0xf bank_mask:0xf bound_ctrl:1
	s_and_saveexec_b64 s[8:9], s[38:39]
	v_cvt_pk_bf16_f32 v1, v1, v8
	ds_write_b32 v218, v1 offset:4288
.LBB0_412:
	s_or_b64 exec, exec, s[8:9]
	s_waitcnt lgkmcnt(6)
	v_add_f32_e32 v1, v22, v23
	v_fmamk_f32 v1, v1, 0x3c000000, v214
	v_rsq_f32_e32 v1, v1
	s_nop 0
	v_mul_f32_e32 v8, v2, v1
	v_mul_f32_e32 v8, v77, v8
	s_nop 1
	v_mov_b32_dpp v9, v8 quad_perm:[1,0,3,2] row_mask:0xf bank_mask:0xf bound_ctrl:1
	s_and_saveexec_b64 s[8:9], s[38:39]
	v_cvt_pk_bf16_f32 v22, v8, v9
	ds_write_b32 v218, v22 offset:4352
.LBB0_414:
	s_or_b64 exec, exec, s[8:9]
	v_mul_f32_e32 v8, v3, v1
	v_mul_f32_e32 v8, v125, v8
	s_nop 1
	v_mov_b32_dpp v9, v8 quad_perm:[1,0,3,2] row_mask:0xf bank_mask:0xf bound_ctrl:1
	s_and_saveexec_b64 s[8:9], s[38:39]
	v_cvt_pk_bf16_f32 v22, v8, v9
	ds_write_b32 v218, v22 offset:4416
.LBB0_416:
	s_or_b64 exec, exec, s[8:9]
	v_mul_f32_e32 v8, v6, v1
	v_mul_f32_e32 v8, v141, v8
	s_nop 1
	v_mov_b32_dpp v9, v8 quad_perm:[1,0,3,2] row_mask:0xf bank_mask:0xf bound_ctrl:1
	s_and_saveexec_b64 s[8:9], s[38:39]
	v_cvt_pk_bf16_f32 v22, v8, v9
	ds_write_b32 v218, v22 offset:4480
.LBB0_418:
	s_or_b64 exec, exec, s[8:9]
	v_mul_f32_e32 v1, v7, v1
	v_mul_f32_e32 v1, v157, v1
	s_nop 1
	v_mov_b32_dpp v8, v1 quad_perm:[1,0,3,2] row_mask:0xf bank_mask:0xf bound_ctrl:1
	s_and_saveexec_b64 s[8:9], s[38:39]
	v_cvt_pk_bf16_f32 v1, v1, v8
	ds_write_b32 v218, v1 offset:4544
.LBB0_420:
	s_or_b64 exec, exec, s[8:9]
	s_waitcnt lgkmcnt(5)
	v_add_f32_e32 v1, v20, v21
	v_fmamk_f32 v1, v1, 0x3c000000, v214
	v_rsq_f32_e32 v1, v1
	s_nop 0
	v_mul_f32_e32 v8, v2, v1
	v_mul_f32_e32 v8, v78, v8
	s_nop 1
	v_mov_b32_dpp v9, v8 quad_perm:[1,0,3,2] row_mask:0xf bank_mask:0xf bound_ctrl:1
	s_and_saveexec_b64 s[8:9], s[38:39]
	v_cvt_pk_bf16_f32 v20, v8, v9
	ds_write_b32 v218, v20 offset:4608
.LBB0_422:
	s_or_b64 exec, exec, s[8:9]
	v_mul_f32_e32 v8, v3, v1
	v_mul_f32_e32 v8, v126, v8
	s_nop 1
	v_mov_b32_dpp v9, v8 quad_perm:[1,0,3,2] row_mask:0xf bank_mask:0xf bound_ctrl:1
	s_and_saveexec_b64 s[8:9], s[38:39]
	v_cvt_pk_bf16_f32 v20, v8, v9
	ds_write_b32 v218, v20 offset:4672
.LBB0_424:
	s_or_b64 exec, exec, s[8:9]
	v_mul_f32_e32 v8, v6, v1
	v_mul_f32_e32 v8, v142, v8
	s_nop 1
	v_mov_b32_dpp v9, v8 quad_perm:[1,0,3,2] row_mask:0xf bank_mask:0xf bound_ctrl:1
	s_and_saveexec_b64 s[8:9], s[38:39]
	v_cvt_pk_bf16_f32 v20, v8, v9
	ds_write_b32 v218, v20 offset:4736
.LBB0_426:
	s_or_b64 exec, exec, s[8:9]
	v_mul_f32_e32 v1, v7, v1
	v_mul_f32_e32 v1, v158, v1
	s_nop 1
	v_mov_b32_dpp v8, v1 quad_perm:[1,0,3,2] row_mask:0xf bank_mask:0xf bound_ctrl:1
	s_and_saveexec_b64 s[8:9], s[38:39]
	v_cvt_pk_bf16_f32 v1, v1, v8
	ds_write_b32 v218, v1 offset:4800
.LBB0_428:
	s_or_b64 exec, exec, s[8:9]
	s_waitcnt lgkmcnt(4)
	v_add_f32_e32 v1, v18, v19
	v_fmamk_f32 v1, v1, 0x3c000000, v214
	v_rsq_f32_e32 v1, v1
	s_nop 0
	v_mul_f32_e32 v8, v2, v1
	v_mul_f32_e32 v8, v79, v8
	s_nop 1
	v_mov_b32_dpp v9, v8 quad_perm:[1,0,3,2] row_mask:0xf bank_mask:0xf bound_ctrl:1
	s_and_saveexec_b64 s[8:9], s[38:39]
	v_cvt_pk_bf16_f32 v18, v8, v9
	ds_write_b32 v218, v18 offset:4864
.LBB0_430:
	s_or_b64 exec, exec, s[8:9]
	v_mul_f32_e32 v8, v3, v1
	v_mul_f32_e32 v8, v127, v8
	s_nop 1
	v_mov_b32_dpp v9, v8 quad_perm:[1,0,3,2] row_mask:0xf bank_mask:0xf bound_ctrl:1
	s_and_saveexec_b64 s[8:9], s[38:39]
	v_cvt_pk_bf16_f32 v18, v8, v9
	ds_write_b32 v218, v18 offset:4928
.LBB0_432:
	s_or_b64 exec, exec, s[8:9]
	v_mul_f32_e32 v8, v6, v1
	v_mul_f32_e32 v8, v143, v8
	s_nop 1
	v_mov_b32_dpp v9, v8 quad_perm:[1,0,3,2] row_mask:0xf bank_mask:0xf bound_ctrl:1
	s_and_saveexec_b64 s[8:9], s[38:39]
	v_cvt_pk_bf16_f32 v18, v8, v9
	ds_write_b32 v218, v18 offset:4992
.LBB0_434:
	s_or_b64 exec, exec, s[8:9]
	v_mul_f32_e32 v1, v7, v1
	v_mul_f32_e32 v1, v159, v1
	s_nop 1
	v_mov_b32_dpp v8, v1 quad_perm:[1,0,3,2] row_mask:0xf bank_mask:0xf bound_ctrl:1
	s_and_saveexec_b64 s[8:9], s[38:39]
	v_cvt_pk_bf16_f32 v1, v1, v8
	ds_write_b32 v218, v1 offset:5056
.LBB0_436:
	s_or_b64 exec, exec, s[8:9]
	s_waitcnt lgkmcnt(3)
	v_add_f32_e32 v1, v16, v17
	v_fmamk_f32 v1, v1, 0x3c000000, v214
	v_rsq_f32_e32 v1, v1
	s_nop 0
	v_mul_f32_e32 v8, v2, v1
	v_mul_f32_e32 v8, v80, v8
	s_nop 1
	v_mov_b32_dpp v9, v8 quad_perm:[1,0,3,2] row_mask:0xf bank_mask:0xf bound_ctrl:1
	s_and_saveexec_b64 s[8:9], s[38:39]
	v_cvt_pk_bf16_f32 v16, v8, v9
	ds_write_b32 v218, v16 offset:6144
.LBB0_438:
	s_or_b64 exec, exec, s[8:9]
	v_mul_f32_e32 v8, v3, v1
	v_mul_f32_e32 v8, v128, v8
	s_nop 1
	v_mov_b32_dpp v9, v8 quad_perm:[1,0,3,2] row_mask:0xf bank_mask:0xf bound_ctrl:1
	s_and_saveexec_b64 s[8:9], s[38:39]
	v_cvt_pk_bf16_f32 v16, v8, v9
	ds_write_b32 v218, v16 offset:6208
.LBB0_440:
	s_or_b64 exec, exec, s[8:9]
	v_mul_f32_e32 v8, v6, v1
	v_mul_f32_e32 v8, v144, v8
	s_nop 1
	v_mov_b32_dpp v9, v8 quad_perm:[1,0,3,2] row_mask:0xf bank_mask:0xf bound_ctrl:1
	s_and_saveexec_b64 s[8:9], s[38:39]
	v_cvt_pk_bf16_f32 v16, v8, v9
	ds_write_b32 v218, v16 offset:6272
.LBB0_442:
	s_or_b64 exec, exec, s[8:9]
	v_mul_f32_e32 v1, v7, v1
	v_mul_f32_e32 v1, v160, v1
	s_nop 1
	v_mov_b32_dpp v8, v1 quad_perm:[1,0,3,2] row_mask:0xf bank_mask:0xf bound_ctrl:1
	s_and_saveexec_b64 s[8:9], s[38:39]
	v_cvt_pk_bf16_f32 v1, v1, v8
	ds_write_b32 v218, v1 offset:6336
.LBB0_444:
	s_or_b64 exec, exec, s[8:9]
	s_waitcnt lgkmcnt(2)
	v_add_f32_e32 v1, v14, v15
	v_fmamk_f32 v1, v1, 0x3c000000, v214
	v_rsq_f32_e32 v1, v1
	s_nop 0
	v_mul_f32_e32 v8, v2, v1
	v_mul_f32_e32 v8, v81, v8
	s_nop 1
	v_mov_b32_dpp v9, v8 quad_perm:[1,0,3,2] row_mask:0xf bank_mask:0xf bound_ctrl:1
	s_and_saveexec_b64 s[8:9], s[38:39]
	v_cvt_pk_bf16_f32 v14, v8, v9
	ds_write_b32 v218, v14 offset:6400
.LBB0_446:
	s_or_b64 exec, exec, s[8:9]
	v_mul_f32_e32 v8, v3, v1
	v_mul_f32_e32 v8, v129, v8
	s_nop 1
	v_mov_b32_dpp v9, v8 quad_perm:[1,0,3,2] row_mask:0xf bank_mask:0xf bound_ctrl:1
	s_and_saveexec_b64 s[8:9], s[38:39]
	v_cvt_pk_bf16_f32 v14, v8, v9
	ds_write_b32 v218, v14 offset:6464
.LBB0_448:
	s_or_b64 exec, exec, s[8:9]
	v_mul_f32_e32 v8, v6, v1
	v_mul_f32_e32 v8, v145, v8
	s_nop 1
	v_mov_b32_dpp v9, v8 quad_perm:[1,0,3,2] row_mask:0xf bank_mask:0xf bound_ctrl:1
	s_and_saveexec_b64 s[8:9], s[38:39]
	v_cvt_pk_bf16_f32 v14, v8, v9
	ds_write_b32 v218, v14 offset:6528
.LBB0_450:
	s_or_b64 exec, exec, s[8:9]
	v_mul_f32_e32 v1, v7, v1
	v_mul_f32_e32 v1, v161, v1
	s_nop 1
	v_mov_b32_dpp v8, v1 quad_perm:[1,0,3,2] row_mask:0xf bank_mask:0xf bound_ctrl:1
	s_and_saveexec_b64 s[8:9], s[38:39]
	v_cvt_pk_bf16_f32 v1, v1, v8
	ds_write_b32 v218, v1 offset:6592
.LBB0_452:
	s_or_b64 exec, exec, s[8:9]
	s_waitcnt lgkmcnt(1)
	v_add_f32_e32 v1, v12, v13
	v_fmamk_f32 v1, v1, 0x3c000000, v214
	v_rsq_f32_e32 v1, v1
	s_nop 0
	v_mul_f32_e32 v8, v2, v1
	v_mul_f32_e32 v8, v82, v8
	s_nop 1
	v_mov_b32_dpp v9, v8 quad_perm:[1,0,3,2] row_mask:0xf bank_mask:0xf bound_ctrl:1
	s_and_saveexec_b64 s[8:9], s[38:39]
	v_cvt_pk_bf16_f32 v12, v8, v9
	ds_write_b32 v218, v12 offset:6656
.LBB0_454:
	s_or_b64 exec, exec, s[8:9]
	v_mul_f32_e32 v8, v3, v1
	v_mul_f32_e32 v8, v130, v8
	s_nop 1
	v_mov_b32_dpp v9, v8 quad_perm:[1,0,3,2] row_mask:0xf bank_mask:0xf bound_ctrl:1
	s_and_saveexec_b64 s[8:9], s[38:39]
	v_cvt_pk_bf16_f32 v12, v8, v9
	ds_write_b32 v218, v12 offset:6720
.LBB0_456:
	s_or_b64 exec, exec, s[8:9]
	v_mul_f32_e32 v8, v6, v1
	v_mul_f32_e32 v8, v146, v8
	s_nop 1
	v_mov_b32_dpp v9, v8 quad_perm:[1,0,3,2] row_mask:0xf bank_mask:0xf bound_ctrl:1
	s_and_saveexec_b64 s[8:9], s[38:39]
	v_cvt_pk_bf16_f32 v12, v8, v9
	ds_write_b32 v218, v12 offset:6784
.LBB0_458:
	s_or_b64 exec, exec, s[8:9]
	v_mul_f32_e32 v1, v7, v1
	v_mul_f32_e32 v1, v162, v1
	s_nop 1
	v_mov_b32_dpp v8, v1 quad_perm:[1,0,3,2] row_mask:0xf bank_mask:0xf bound_ctrl:1
	s_and_saveexec_b64 s[8:9], s[38:39]
	v_cvt_pk_bf16_f32 v1, v1, v8
	ds_write_b32 v218, v1 offset:6848
.LBB0_460:
	s_or_b64 exec, exec, s[8:9]
	s_waitcnt lgkmcnt(0)
	v_add_f32_e32 v1, v10, v11
	v_fmamk_f32 v1, v1, 0x3c000000, v214
	v_rsq_f32_e32 v1, v1
	s_nop 0
	v_mul_f32_e32 v2, v2, v1
	v_mul_f32_e32 v2, v83, v2
	s_nop 1
	v_mov_b32_dpp v8, v2 quad_perm:[1,0,3,2] row_mask:0xf bank_mask:0xf bound_ctrl:1
	s_and_saveexec_b64 s[8:9], s[38:39]
	v_cvt_pk_bf16_f32 v2, v2, v8
	ds_write_b32 v218, v2 offset:6912
.LBB0_462:
	s_or_b64 exec, exec, s[8:9]
	v_mul_f32_e32 v2, v3, v1
	v_mul_f32_e32 v2, v131, v2
	s_nop 1
	v_mov_b32_dpp v3, v2 quad_perm:[1,0,3,2] row_mask:0xf bank_mask:0xf bound_ctrl:1
	s_and_saveexec_b64 s[8:9], s[38:39]
	v_cvt_pk_bf16_f32 v8, v2, v3
	ds_write_b32 v218, v8 offset:6976
.LBB0_464:
	s_or_b64 exec, exec, s[8:9]
	v_mul_f32_e32 v2, v6, v1
	v_mul_f32_e32 v2, v147, v2
	s_nop 1
	v_mov_b32_dpp v3, v2 quad_perm:[1,0,3,2] row_mask:0xf bank_mask:0xf bound_ctrl:1
	s_and_saveexec_b64 s[8:9], s[38:39]
	v_cvt_pk_bf16_f32 v6, v2, v3
	ds_write_b32 v218, v6 offset:7040
.LBB0_466:
	s_or_b64 exec, exec, s[8:9]
	v_mul_f32_e32 v1, v7, v1
	v_mul_f32_e32 v1, v163, v1
	s_nop 1
	v_mov_b32_dpp v2, v1 quad_perm:[1,0,3,2] row_mask:0xf bank_mask:0xf bound_ctrl:1
	s_and_saveexec_b64 s[8:9], s[38:39]
	s_xor_b64 s[8:9], exec, s[8:9]
	v_cvt_pk_bf16_f32 v1, v1, v2
	ds_write_b32 v218, v1 offset:7104
	s_or_b64 exec, exec, s[8:9]
	s_waitcnt lgkmcnt(0)
	v_and_b32_e32 v219, 63, v0
	v_and_b32_e32 v224, 0x1c0, v0
	v_lshlrev_b32_e32 v224, 7, v224
	v_lshl_add_u32 v224, v219, 4, v224
	ds_read_b128 v[232:235], v224
	ds_read_b128 v[236:239], v224 offset:1024
	ds_read_b128 v[240:243], v224 offset:2048
	ds_read_b128 v[244:247], v224 offset:3072
	v_lshrrev_b32_e32 v226, 4, v219
	v_lshlrev_b32_e32 v226, 12, v226
	v_and_b32_e32 v225, 15, v219
	v_lshl_add_u32 v226, v225, 4, v226
	v_and_b32_e32 v225, 31, v219
	v_lshlrev_b32_e32 v225, 1, v225
	v_sub_u32_e32 v226, v226, v225
	v_and_b32_e32 v225, 32, v219
	v_lshlrev_b32_e32 v225, 9, v225
	v_sub_u32_e32 v226, v226, v225
	v_ashrrev_i32_e32 v227, 31, v226
	v_lshl_add_u64 v[228:229], v[4:5], 0, v[226:227]
	s_mov_b64 s[8:9], 0x4000
	v_lshl_add_u64 v[230:231], v[228:229], 0, s[8:9]
	s_waitcnt lgkmcnt(3)
	global_store_dwordx4 v[228:229], v[232:235], off
	v_lshl_add_u64 v[228:229], v[230:231], 0, s[8:9]
	s_waitcnt lgkmcnt(2)
	global_store_dwordx4 v[230:231], v[236:239], off
	v_lshl_add_u64 v[230:231], v[228:229], 0, s[8:9]
	s_waitcnt lgkmcnt(1)
	global_store_dwordx4 v[228:229], v[240:243], off
	v_lshl_add_u64 v[228:229], v[230:231], 0, s[8:9]
	s_waitcnt lgkmcnt(0)
	global_store_dwordx4 v[230:231], v[244:247], off
	ds_read_b128 v[232:235], v224 offset:4096
	ds_read_b128 v[236:239], v224 offset:5120
	ds_read_b128 v[240:243], v224 offset:6144
	ds_read_b128 v[244:247], v224 offset:7168
	v_lshl_add_u64 v[230:231], v[228:229], 0, s[8:9]
	s_waitcnt lgkmcnt(3)
	global_store_dwordx4 v[228:229], v[232:235], off
	v_lshl_add_u64 v[228:229], v[230:231], 0, s[8:9]
	s_waitcnt lgkmcnt(2)
	global_store_dwordx4 v[230:231], v[236:239], off
	v_lshl_add_u64 v[230:231], v[228:229], 0, s[8:9]
	s_waitcnt lgkmcnt(1)
	global_store_dwordx4 v[228:229], v[240:243], off
	s_waitcnt lgkmcnt(0)
	global_store_dwordx4 v[230:231], v[244:247], off
	s_branch .LBB0_297

.LBB0_517:
	s_and_saveexec_b64 s[4:5], s[40:41]
	v_rcp_f32_e32 v68, v196
	ds_write_b32 v184, v68 offset:128
	s_or_b64 exec, exec, s[4:5]
	s_ashr_i32 s5, s33, 31
	v_readlane_b32 s6, v255, 55
	v_readlane_b32 s7, v255, 56
	s_add_u32 s4, s6, s33
	s_addc_u32 s5, s7, s5
	s_lshl_b64 s[4:5], s[4:5], 12
	v_readlane_b32 s6, v252, 59
	s_add_u32 s6, s6, s4
	v_readlane_b32 s4, v252, 60
	s_addc_u32 s7, s4, s5
	v_readlane_b32 s4, v255, 57
	v_readlane_b32 s5, v255, 58
	s_ashr_i32 s5, s4, 31
	s_waitcnt lgkmcnt(0)
	v_add_u32_e32 v34, s35, v34
	s_lshl_b64 s[4:5], s[4:5], 1
	ds_read_b128 v[80:83], v34 offset:128
	ds_read_b128 v[76:79], v34 offset:160
	ds_read_b128 v[72:75], v34 offset:192
	ds_read_b128 v[68:71], v34 offset:224
	s_add_u32 s4, s6, s4
	v_and_b32_e32 v34, 1, v165
	s_addc_u32 s5, s7, s5
	v_cmp_eq_u32_e64 s[38:39], 0, v34
	v_lshlrev_b32_e32 v34, 1, v1
	s_waitcnt lgkmcnt(0)
	v_lshlrev_b32_e32 v84, 14, v166
	v_lshl_add_u64 v[86:87], s[4:5], 0, v[34:35]
	v_mov_b32_e32 v85, v35
	s_waitcnt lgkmcnt(3)
	v_mul_f32_e32 v52, v52, v80
	v_lshl_add_u64 v[86:87], v[86:87], 0, v[84:85]
	s_mov_b64 s[4:5], 0xb00
	v_lshl_add_u64 v[84:85], v[86:87], 0, s[4:5]
	v_mov_b32_dpp v1, v52 quad_perm:[1,0,3,2] row_mask:0xf bank_mask:0xf bound_ctrl:1
	v_and_b32_e32 v218, 0x1c0, v0
	v_lshlrev_b32_e32 v218, 7, v218
	v_and_b32_e32 v219, 32, v0
	v_lshl_add_u32 v218, v219, 5, v218
	v_and_b32_e32 v219, 31, v0
	v_lshl_add_u32 v218, v219, 1, v218
	s_and_saveexec_b64 s[4:5], s[38:39]
	v_cvt_pk_bf16_f32 v1, v52, v1
	ds_write_b32 v218, v1 offset:0
.LBB0_521:
	s_or_b64 exec, exec, s[4:5]
	v_mul_f32_e32 v1, v36, v80
	s_nop 1
	v_mov_b32_dpp v34, v1 quad_perm:[1,0,3,2] row_mask:0xf bank_mask:0xf bound_ctrl:1
	s_and_saveexec_b64 s[4:5], s[38:39]
	v_cvt_pk_bf16_f32 v1, v1, v34
	ds_write_b32 v218, v1 offset:64
.LBB0_523:
	s_or_b64 exec, exec, s[4:5]
	v_mul_f32_e32 v1, v18, v80
	s_nop 1
	v_mov_b32_dpp v18, v1 quad_perm:[1,0,3,2] row_mask:0xf bank_mask:0xf bound_ctrl:1
	s_and_saveexec_b64 s[4:5], s[38:39]
	v_cvt_pk_bf16_f32 v1, v1, v18
	ds_write_b32 v218, v1 offset:128
.LBB0_525:
	s_or_b64 exec, exec, s[4:5]
	v_mul_f32_e32 v1, v2, v80
	s_nop 1
	v_mov_b32_dpp v2, v1 quad_perm:[1,0,3,2] row_mask:0xf bank_mask:0xf bound_ctrl:1
	s_and_saveexec_b64 s[4:5], s[38:39]
	v_cvt_pk_bf16_f32 v1, v1, v2
	ds_write_b32 v218, v1 offset:192
.LBB0_527:
	s_or_b64 exec, exec, s[4:5]
	v_mul_f32_e32 v1, v53, v81
	s_nop 1
	v_mov_b32_dpp v2, v1 quad_perm:[1,0,3,2] row_mask:0xf bank_mask:0xf bound_ctrl:1
	s_and_saveexec_b64 s[4:5], s[38:39]
	v_cvt_pk_bf16_f32 v1, v1, v2
	ds_write_b32 v218, v1 offset:256
.LBB0_529:
	s_or_b64 exec, exec, s[4:5]
	v_mul_f32_e32 v1, v37, v81
	s_nop 1
	v_mov_b32_dpp v2, v1 quad_perm:[1,0,3,2] row_mask:0xf bank_mask:0xf bound_ctrl:1
	s_and_saveexec_b64 s[4:5], s[38:39]
	v_cvt_pk_bf16_f32 v1, v1, v2
	ds_write_b32 v218, v1 offset:320
.LBB0_531:
	s_or_b64 exec, exec, s[4:5]
	v_mul_f32_e32 v1, v19, v81
	s_nop 1
	v_mov_b32_dpp v2, v1 quad_perm:[1,0,3,2] row_mask:0xf bank_mask:0xf bound_ctrl:1
	s_and_saveexec_b64 s[4:5], s[38:39]
	v_cvt_pk_bf16_f32 v1, v1, v2
	ds_write_b32 v218, v1 offset:384
.LBB0_533:
	s_or_b64 exec, exec, s[4:5]
	v_mul_f32_e32 v1, v3, v81
	s_nop 1
	v_mov_b32_dpp v2, v1 quad_perm:[1,0,3,2] row_mask:0xf bank_mask:0xf bound_ctrl:1
	s_and_saveexec_b64 s[4:5], s[38:39]
	v_cvt_pk_bf16_f32 v1, v1, v2
	ds_write_b32 v218, v1 offset:448
.LBB0_535:
	s_or_b64 exec, exec, s[4:5]
	v_mul_f32_e32 v1, v54, v82
	s_nop 1
	v_mov_b32_dpp v2, v1 quad_perm:[1,0,3,2] row_mask:0xf bank_mask:0xf bound_ctrl:1
	s_and_saveexec_b64 s[4:5], s[38:39]
	v_cvt_pk_bf16_f32 v1, v1, v2
	ds_write_b32 v218, v1 offset:512
.LBB0_537:
	s_or_b64 exec, exec, s[4:5]
	v_mul_f32_e32 v1, v38, v82
	s_nop 1
	v_mov_b32_dpp v2, v1 quad_perm:[1,0,3,2] row_mask:0xf bank_mask:0xf bound_ctrl:1
	s_and_saveexec_b64 s[4:5], s[38:39]
	v_cvt_pk_bf16_f32 v1, v1, v2
	ds_write_b32 v218, v1 offset:576
.LBB0_539:
	s_or_b64 exec, exec, s[4:5]
	v_mul_f32_e32 v1, v20, v82
	s_nop 1
	v_mov_b32_dpp v2, v1 quad_perm:[1,0,3,2] row_mask:0xf bank_mask:0xf bound_ctrl:1
	s_and_saveexec_b64 s[4:5], s[38:39]
	v_cvt_pk_bf16_f32 v1, v1, v2
	ds_write_b32 v218, v1 offset:640
.LBB0_541:
	s_or_b64 exec, exec, s[4:5]
	v_mul_f32_e32 v1, v4, v82
	s_nop 1
	v_mov_b32_dpp v2, v1 quad_perm:[1,0,3,2] row_mask:0xf bank_mask:0xf bound_ctrl:1
	s_and_saveexec_b64 s[4:5], s[38:39]
	v_cvt_pk_bf16_f32 v1, v1, v2
	ds_write_b32 v218, v1 offset:704
.LBB0_543:
	s_or_b64 exec, exec, s[4:5]
	v_mul_f32_e32 v1, v55, v83
	s_nop 1
	v_mov_b32_dpp v2, v1 quad_perm:[1,0,3,2] row_mask:0xf bank_mask:0xf bound_ctrl:1
	s_and_saveexec_b64 s[4:5], s[38:39]
	v_cvt_pk_bf16_f32 v1, v1, v2
	ds_write_b32 v218, v1 offset:768
.LBB0_545:
	s_or_b64 exec, exec, s[4:5]
	v_mul_f32_e32 v1, v39, v83
	s_nop 1
	v_mov_b32_dpp v2, v1 quad_perm:[1,0,3,2] row_mask:0xf bank_mask:0xf bound_ctrl:1
	s_and_saveexec_b64 s[4:5], s[38:39]
	v_cvt_pk_bf16_f32 v1, v1, v2
	ds_write_b32 v218, v1 offset:832
.LBB0_547:
	s_or_b64 exec, exec, s[4:5]
	v_mul_f32_e32 v1, v21, v83
	s_nop 1
	v_mov_b32_dpp v2, v1 quad_perm:[1,0,3,2] row_mask:0xf bank_mask:0xf bound_ctrl:1
	s_and_saveexec_b64 s[4:5], s[38:39]
	v_cvt_pk_bf16_f32 v1, v1, v2
	ds_write_b32 v218, v1 offset:896
.LBB0_549:
	s_or_b64 exec, exec, s[4:5]
	v_mul_f32_e32 v1, v5, v83
	s_nop 1
	v_mov_b32_dpp v2, v1 quad_perm:[1,0,3,2] row_mask:0xf bank_mask:0xf bound_ctrl:1
	s_and_saveexec_b64 s[4:5], s[38:39]
	v_cvt_pk_bf16_f32 v1, v1, v2
	ds_write_b32 v218, v1 offset:960
.LBB0_551:
	s_or_b64 exec, exec, s[4:5]
	s_waitcnt lgkmcnt(2)
	v_mul_f32_e32 v1, v56, v76
	s_nop 1
	v_mov_b32_dpp v2, v1 quad_perm:[1,0,3,2] row_mask:0xf bank_mask:0xf bound_ctrl:1
	s_and_saveexec_b64 s[4:5], s[38:39]
	v_cvt_pk_bf16_f32 v1, v1, v2
	ds_write_b32 v218, v1 offset:2048
.LBB0_553:
	s_or_b64 exec, exec, s[4:5]
	v_mul_f32_e32 v1, v40, v76
	s_nop 1
	v_mov_b32_dpp v2, v1 quad_perm:[1,0,3,2] row_mask:0xf bank_mask:0xf bound_ctrl:1
	s_and_saveexec_b64 s[4:5], s[38:39]
	v_cvt_pk_bf16_f32 v1, v1, v2
	ds_write_b32 v218, v1 offset:2112
.LBB0_555:
	s_or_b64 exec, exec, s[4:5]
	v_mul_f32_e32 v1, v22, v76
	s_nop 1
	v_mov_b32_dpp v2, v1 quad_perm:[1,0,3,2] row_mask:0xf bank_mask:0xf bound_ctrl:1
	s_and_saveexec_b64 s[4:5], s[38:39]
	v_cvt_pk_bf16_f32 v1, v1, v2
	ds_write_b32 v218, v1 offset:2176
.LBB0_557:
	s_or_b64 exec, exec, s[4:5]
	v_mul_f32_e32 v1, v6, v76
	s_nop 1
	v_mov_b32_dpp v2, v1 quad_perm:[1,0,3,2] row_mask:0xf bank_mask:0xf bound_ctrl:1
	s_and_saveexec_b64 s[4:5], s[38:39]
	v_cvt_pk_bf16_f32 v1, v1, v2
	ds_write_b32 v218, v1 offset:2240
.LBB0_559:
	s_or_b64 exec, exec, s[4:5]
	v_mul_f32_e32 v1, v57, v77
	s_nop 1
	v_mov_b32_dpp v2, v1 quad_perm:[1,0,3,2] row_mask:0xf bank_mask:0xf bound_ctrl:1
	s_and_saveexec_b64 s[4:5], s[38:39]
	v_cvt_pk_bf16_f32 v1, v1, v2
	ds_write_b32 v218, v1 offset:2304
.LBB0_561:
	s_or_b64 exec, exec, s[4:5]
	v_mul_f32_e32 v1, v41, v77
	s_nop 1
	v_mov_b32_dpp v2, v1 quad_perm:[1,0,3,2] row_mask:0xf bank_mask:0xf bound_ctrl:1
	s_and_saveexec_b64 s[4:5], s[38:39]
	v_cvt_pk_bf16_f32 v1, v1, v2
	ds_write_b32 v218, v1 offset:2368
.LBB0_563:
	s_or_b64 exec, exec, s[4:5]
	v_mul_f32_e32 v1, v23, v77
	s_nop 1
	v_mov_b32_dpp v2, v1 quad_perm:[1,0,3,2] row_mask:0xf bank_mask:0xf bound_ctrl:1
	s_and_saveexec_b64 s[4:5], s[38:39]
	v_cvt_pk_bf16_f32 v1, v1, v2
	ds_write_b32 v218, v1 offset:2432
.LBB0_565:
	s_or_b64 exec, exec, s[4:5]
	v_mul_f32_e32 v1, v7, v77
	s_nop 1
	v_mov_b32_dpp v2, v1 quad_perm:[1,0,3,2] row_mask:0xf bank_mask:0xf bound_ctrl:1
	s_and_saveexec_b64 s[4:5], s[38:39]
	v_cvt_pk_bf16_f32 v1, v1, v2
	ds_write_b32 v218, v1 offset:2496
.LBB0_567:
	s_or_b64 exec, exec, s[4:5]
	v_mul_f32_e32 v1, v58, v78
	s_nop 1
	v_mov_b32_dpp v2, v1 quad_perm:[1,0,3,2] row_mask:0xf bank_mask:0xf bound_ctrl:1
	s_and_saveexec_b64 s[4:5], s[38:39]
	v_cvt_pk_bf16_f32 v1, v1, v2
	ds_write_b32 v218, v1 offset:2560
.LBB0_569:
	s_or_b64 exec, exec, s[4:5]
	v_mul_f32_e32 v1, v42, v78
	s_nop 1
	v_mov_b32_dpp v2, v1 quad_perm:[1,0,3,2] row_mask:0xf bank_mask:0xf bound_ctrl:1
	s_and_saveexec_b64 s[4:5], s[38:39]
	v_cvt_pk_bf16_f32 v1, v1, v2
	ds_write_b32 v218, v1 offset:2624
.LBB0_571:
	s_or_b64 exec, exec, s[4:5]
	v_mul_f32_e32 v1, v24, v78
	s_nop 1
	v_mov_b32_dpp v2, v1 quad_perm:[1,0,3,2] row_mask:0xf bank_mask:0xf bound_ctrl:1
	s_and_saveexec_b64 s[4:5], s[38:39]
	v_cvt_pk_bf16_f32 v1, v1, v2
	ds_write_b32 v218, v1 offset:2688
.LBB0_573:
	s_or_b64 exec, exec, s[4:5]
	v_mul_f32_e32 v1, v8, v78
	s_nop 1
	v_mov_b32_dpp v2, v1 quad_perm:[1,0,3,2] row_mask:0xf bank_mask:0xf bound_ctrl:1
	s_and_saveexec_b64 s[4:5], s[38:39]
	v_cvt_pk_bf16_f32 v1, v1, v2
	ds_write_b32 v218, v1 offset:2752
.LBB0_575:
	s_or_b64 exec, exec, s[4:5]
	v_mul_f32_e32 v1, v59, v79
	s_nop 1
	v_mov_b32_dpp v2, v1 quad_perm:[1,0,3,2] row_mask:0xf bank_mask:0xf bound_ctrl:1
	s_and_saveexec_b64 s[4:5], s[38:39]
	v_cvt_pk_bf16_f32 v1, v1, v2
	ds_write_b32 v218, v1 offset:2816
.LBB0_577:
	s_or_b64 exec, exec, s[4:5]
	v_mul_f32_e32 v1, v43, v79
	s_nop 1
	v_mov_b32_dpp v2, v1 quad_perm:[1,0,3,2] row_mask:0xf bank_mask:0xf bound_ctrl:1
	s_and_saveexec_b64 s[4:5], s[38:39]
	v_cvt_pk_bf16_f32 v1, v1, v2
	ds_write_b32 v218, v1 offset:2880
.LBB0_579:
	s_or_b64 exec, exec, s[4:5]
	v_mul_f32_e32 v1, v25, v79
	s_nop 1
	v_mov_b32_dpp v2, v1 quad_perm:[1,0,3,2] row_mask:0xf bank_mask:0xf bound_ctrl:1
	s_and_saveexec_b64 s[4:5], s[38:39]
	v_cvt_pk_bf16_f32 v1, v1, v2
	ds_write_b32 v218, v1 offset:2944
.LBB0_581:
	s_or_b64 exec, exec, s[4:5]
	v_mul_f32_e32 v1, v9, v79
	s_nop 1
	v_mov_b32_dpp v2, v1 quad_perm:[1,0,3,2] row_mask:0xf bank_mask:0xf bound_ctrl:1
	s_and_saveexec_b64 s[4:5], s[38:39]
	v_cvt_pk_bf16_f32 v1, v1, v2
	ds_write_b32 v218, v1 offset:3008
.LBB0_583:
	s_or_b64 exec, exec, s[4:5]
	s_waitcnt lgkmcnt(1)
	v_mul_f32_e32 v1, v60, v72
	s_nop 1
	v_mov_b32_dpp v2, v1 quad_perm:[1,0,3,2] row_mask:0xf bank_mask:0xf bound_ctrl:1
	s_and_saveexec_b64 s[4:5], s[38:39]
	v_cvt_pk_bf16_f32 v1, v1, v2
	ds_write_b32 v218, v1 offset:4096
.LBB0_585:
	s_or_b64 exec, exec, s[4:5]
	v_mul_f32_e32 v1, v44, v72
	s_nop 1
	v_mov_b32_dpp v2, v1 quad_perm:[1,0,3,2] row_mask:0xf bank_mask:0xf bound_ctrl:1
	s_and_saveexec_b64 s[4:5], s[38:39]
	v_cvt_pk_bf16_f32 v1, v1, v2
	ds_write_b32 v218, v1 offset:4160
.LBB0_587:
	s_or_b64 exec, exec, s[4:5]
	v_mul_f32_e32 v1, v26, v72
	s_nop 1
	v_mov_b32_dpp v2, v1 quad_perm:[1,0,3,2] row_mask:0xf bank_mask:0xf bound_ctrl:1
	s_and_saveexec_b64 s[4:5], s[38:39]
	v_cvt_pk_bf16_f32 v1, v1, v2
	ds_write_b32 v218, v1 offset:4224
.LBB0_589:
	s_or_b64 exec, exec, s[4:5]
	v_mul_f32_e32 v1, v10, v72
	s_nop 1
	v_mov_b32_dpp v2, v1 quad_perm:[1,0,3,2] row_mask:0xf bank_mask:0xf bound_ctrl:1
	s_and_saveexec_b64 s[4:5], s[38:39]
	v_cvt_pk_bf16_f32 v1, v1, v2
	ds_write_b32 v218, v1 offset:4288
.LBB0_591:
	s_or_b64 exec, exec, s[4:5]
	v_mul_f32_e32 v1, v61, v73
	s_nop 1
	v_mov_b32_dpp v2, v1 quad_perm:[1,0,3,2] row_mask:0xf bank_mask:0xf bound_ctrl:1
	s_and_saveexec_b64 s[4:5], s[38:39]
	v_cvt_pk_bf16_f32 v1, v1, v2
	ds_write_b32 v218, v1 offset:4352
.LBB0_593:
	s_or_b64 exec, exec, s[4:5]
	v_mul_f32_e32 v1, v45, v73
	s_nop 1
	v_mov_b32_dpp v2, v1 quad_perm:[1,0,3,2] row_mask:0xf bank_mask:0xf bound_ctrl:1
	s_and_saveexec_b64 s[4:5], s[38:39]
	v_cvt_pk_bf16_f32 v1, v1, v2
	ds_write_b32 v218, v1 offset:4416
.LBB0_595:
	s_or_b64 exec, exec, s[4:5]
	v_mul_f32_e32 v1, v27, v73
	s_nop 1
	v_mov_b32_dpp v2, v1 quad_perm:[1,0,3,2] row_mask:0xf bank_mask:0xf bound_ctrl:1
	s_and_saveexec_b64 s[4:5], s[38:39]
	v_cvt_pk_bf16_f32 v1, v1, v2
	ds_write_b32 v218, v1 offset:4480
.LBB0_597:
	s_or_b64 exec, exec, s[4:5]
	v_mul_f32_e32 v1, v11, v73
	s_nop 1
	v_mov_b32_dpp v2, v1 quad_perm:[1,0,3,2] row_mask:0xf bank_mask:0xf bound_ctrl:1
	s_and_saveexec_b64 s[4:5], s[38:39]
	v_cvt_pk_bf16_f32 v1, v1, v2
	ds_write_b32 v218, v1 offset:4544
.LBB0_599:
	s_or_b64 exec, exec, s[4:5]
	v_mul_f32_e32 v1, v62, v74
	s_nop 1
	v_mov_b32_dpp v2, v1 quad_perm:[1,0,3,2] row_mask:0xf bank_mask:0xf bound_ctrl:1
	s_and_saveexec_b64 s[4:5], s[38:39]
	v_cvt_pk_bf16_f32 v1, v1, v2
	ds_write_b32 v218, v1 offset:4608
.LBB0_601:
	s_or_b64 exec, exec, s[4:5]
	v_mul_f32_e32 v1, v46, v74
	s_nop 1
	v_mov_b32_dpp v2, v1 quad_perm:[1,0,3,2] row_mask:0xf bank_mask:0xf bound_ctrl:1
	s_and_saveexec_b64 s[4:5], s[38:39]
	v_cvt_pk_bf16_f32 v1, v1, v2
	ds_write_b32 v218, v1 offset:4672
.LBB0_603:
	s_or_b64 exec, exec, s[4:5]
	v_mul_f32_e32 v1, v28, v74
	s_nop 1
	v_mov_b32_dpp v2, v1 quad_perm:[1,0,3,2] row_mask:0xf bank_mask:0xf bound_ctrl:1
	s_and_saveexec_b64 s[4:5], s[38:39]
	v_cvt_pk_bf16_f32 v1, v1, v2
	ds_write_b32 v218, v1 offset:4736
.LBB0_605:
	s_or_b64 exec, exec, s[4:5]
	v_mul_f32_e32 v1, v12, v74
	s_nop 1
	v_mov_b32_dpp v2, v1 quad_perm:[1,0,3,2] row_mask:0xf bank_mask:0xf bound_ctrl:1
	s_and_saveexec_b64 s[4:5], s[38:39]
	v_cvt_pk_bf16_f32 v1, v1, v2
	ds_write_b32 v218, v1 offset:4800
.LBB0_607:
	s_or_b64 exec, exec, s[4:5]
	v_mul_f32_e32 v1, v63, v75
	s_nop 1
	v_mov_b32_dpp v2, v1 quad_perm:[1,0,3,2] row_mask:0xf bank_mask:0xf bound_ctrl:1
	s_and_saveexec_b64 s[4:5], s[38:39]
	v_cvt_pk_bf16_f32 v1, v1, v2
	ds_write_b32 v218, v1 offset:4864
.LBB0_609:
	s_or_b64 exec, exec, s[4:5]
	v_mul_f32_e32 v1, v47, v75
	s_nop 1
	v_mov_b32_dpp v2, v1 quad_perm:[1,0,3,2] row_mask:0xf bank_mask:0xf bound_ctrl:1
	s_and_saveexec_b64 s[4:5], s[38:39]
	v_cvt_pk_bf16_f32 v1, v1, v2
	ds_write_b32 v218, v1 offset:4928
.LBB0_611:
	s_or_b64 exec, exec, s[4:5]
	v_mul_f32_e32 v1, v29, v75
	s_nop 1
	v_mov_b32_dpp v2, v1 quad_perm:[1,0,3,2] row_mask:0xf bank_mask:0xf bound_ctrl:1
	s_and_saveexec_b64 s[4:5], s[38:39]
	v_cvt_pk_bf16_f32 v1, v1, v2
	ds_write_b32 v218, v1 offset:4992
.LBB0_613:
	s_or_b64 exec, exec, s[4:5]
	v_mul_f32_e32 v1, v13, v75
	s_nop 1
	v_mov_b32_dpp v2, v1 quad_perm:[1,0,3,2] row_mask:0xf bank_mask:0xf bound_ctrl:1
	s_and_saveexec_b64 s[4:5], s[38:39]
	v_cvt_pk_bf16_f32 v1, v1, v2
	ds_write_b32 v218, v1 offset:5056
.LBB0_615:
	s_or_b64 exec, exec, s[4:5]
	s_waitcnt lgkmcnt(0)
	v_mul_f32_e32 v1, v64, v68
	s_nop 1
	v_mov_b32_dpp v2, v1 quad_perm:[1,0,3,2] row_mask:0xf bank_mask:0xf bound_ctrl:1
	s_and_saveexec_b64 s[4:5], s[38:39]
	v_cvt_pk_bf16_f32 v1, v1, v2
	ds_write_b32 v218, v1 offset:6144
.LBB0_617:
	s_or_b64 exec, exec, s[4:5]
	v_mul_f32_e32 v1, v48, v68
	s_nop 1
	v_mov_b32_dpp v2, v1 quad_perm:[1,0,3,2] row_mask:0xf bank_mask:0xf bound_ctrl:1
	s_and_saveexec_b64 s[4:5], s[38:39]
	v_cvt_pk_bf16_f32 v1, v1, v2
	ds_write_b32 v218, v1 offset:6208
.LBB0_619:
	s_or_b64 exec, exec, s[4:5]
	v_mul_f32_e32 v1, v30, v68
	s_nop 1
	v_mov_b32_dpp v2, v1 quad_perm:[1,0,3,2] row_mask:0xf bank_mask:0xf bound_ctrl:1
	s_and_saveexec_b64 s[4:5], s[38:39]
	v_cvt_pk_bf16_f32 v1, v1, v2
	ds_write_b32 v218, v1 offset:6272
.LBB0_621:
	s_or_b64 exec, exec, s[4:5]
	v_mul_f32_e32 v1, v14, v68
	s_nop 1
	v_mov_b32_dpp v2, v1 quad_perm:[1,0,3,2] row_mask:0xf bank_mask:0xf bound_ctrl:1
	s_and_saveexec_b64 s[4:5], s[38:39]
	v_cvt_pk_bf16_f32 v1, v1, v2
	ds_write_b32 v218, v1 offset:6336
.LBB0_623:
	s_or_b64 exec, exec, s[4:5]
	v_mul_f32_e32 v1, v65, v69
	s_nop 1
	v_mov_b32_dpp v2, v1 quad_perm:[1,0,3,2] row_mask:0xf bank_mask:0xf bound_ctrl:1
	s_and_saveexec_b64 s[4:5], s[38:39]
	v_cvt_pk_bf16_f32 v1, v1, v2
	ds_write_b32 v218, v1 offset:6400
.LBB0_625:
	s_or_b64 exec, exec, s[4:5]
	v_mul_f32_e32 v1, v49, v69
	s_nop 1
	v_mov_b32_dpp v2, v1 quad_perm:[1,0,3,2] row_mask:0xf bank_mask:0xf bound_ctrl:1
	s_and_saveexec_b64 s[4:5], s[38:39]
	v_cvt_pk_bf16_f32 v1, v1, v2
	ds_write_b32 v218, v1 offset:6464
.LBB0_627:
	s_or_b64 exec, exec, s[4:5]
	v_mul_f32_e32 v1, v31, v69
	s_nop 1
	v_mov_b32_dpp v2, v1 quad_perm:[1,0,3,2] row_mask:0xf bank_mask:0xf bound_ctrl:1
	s_and_saveexec_b64 s[4:5], s[38:39]
	v_cvt_pk_bf16_f32 v1, v1, v2
	ds_write_b32 v218, v1 offset:6528
.LBB0_629:
	s_or_b64 exec, exec, s[4:5]
	v_mul_f32_e32 v1, v15, v69
	s_nop 1
	v_mov_b32_dpp v2, v1 quad_perm:[1,0,3,2] row_mask:0xf bank_mask:0xf bound_ctrl:1
	s_and_saveexec_b64 s[4:5], s[38:39]
	v_cvt_pk_bf16_f32 v1, v1, v2
	ds_write_b32 v218, v1 offset:6592
.LBB0_631:
	s_or_b64 exec, exec, s[4:5]
	v_mul_f32_e32 v1, v66, v70
	s_nop 1
	v_mov_b32_dpp v2, v1 quad_perm:[1,0,3,2] row_mask:0xf bank_mask:0xf bound_ctrl:1
	s_and_saveexec_b64 s[4:5], s[38:39]
	v_cvt_pk_bf16_f32 v1, v1, v2
	ds_write_b32 v218, v1 offset:6656
.LBB0_633:
	s_or_b64 exec, exec, s[4:5]
	v_mul_f32_e32 v1, v50, v70
	s_nop 1
	v_mov_b32_dpp v2, v1 quad_perm:[1,0,3,2] row_mask:0xf bank_mask:0xf bound_ctrl:1
	s_and_saveexec_b64 s[4:5], s[38:39]
	v_cvt_pk_bf16_f32 v1, v1, v2
	ds_write_b32 v218, v1 offset:6720
.LBB0_635:
	s_or_b64 exec, exec, s[4:5]
	v_mul_f32_e32 v1, v32, v70
	s_nop 1
	v_mov_b32_dpp v2, v1 quad_perm:[1,0,3,2] row_mask:0xf bank_mask:0xf bound_ctrl:1
	s_and_saveexec_b64 s[4:5], s[38:39]
	v_cvt_pk_bf16_f32 v1, v1, v2
	ds_write_b32 v218, v1 offset:6784
.LBB0_637:
	s_or_b64 exec, exec, s[4:5]
	v_mul_f32_e32 v1, v16, v70
	s_nop 1
	v_mov_b32_dpp v2, v1 quad_perm:[1,0,3,2] row_mask:0xf bank_mask:0xf bound_ctrl:1
	s_and_saveexec_b64 s[4:5], s[38:39]
	v_cvt_pk_bf16_f32 v1, v1, v2
	ds_write_b32 v218, v1 offset:6848
.LBB0_639:
	s_or_b64 exec, exec, s[4:5]
	v_mul_f32_e32 v1, v67, v71
	s_nop 1
	v_mov_b32_dpp v2, v1 quad_perm:[1,0,3,2] row_mask:0xf bank_mask:0xf bound_ctrl:1
	s_and_saveexec_b64 s[4:5], s[38:39]
	v_cvt_pk_bf16_f32 v1, v1, v2
	ds_write_b32 v218, v1 offset:6912
.LBB0_641:
	s_or_b64 exec, exec, s[4:5]
	v_mul_f32_e32 v1, v51, v71
	s_nop 1
	v_mov_b32_dpp v2, v1 quad_perm:[1,0,3,2] row_mask:0xf bank_mask:0xf bound_ctrl:1
	s_and_saveexec_b64 s[4:5], s[38:39]
	v_cvt_pk_bf16_f32 v1, v1, v2
	ds_write_b32 v218, v1 offset:6976
.LBB0_643:
	s_or_b64 exec, exec, s[4:5]
	v_mul_f32_e32 v1, v33, v71
	s_nop 1
	v_mov_b32_dpp v2, v1 quad_perm:[1,0,3,2] row_mask:0xf bank_mask:0xf bound_ctrl:1
	s_and_saveexec_b64 s[4:5], s[38:39]
	v_cvt_pk_bf16_f32 v1, v1, v2
	ds_write_b32 v218, v1 offset:7040
.LBB0_645:
	s_or_b64 exec, exec, s[4:5]
	v_mul_f32_e32 v1, v17, v71
	s_nop 1
	v_mov_b32_dpp v2, v1 quad_perm:[1,0,3,2] row_mask:0xf bank_mask:0xf bound_ctrl:1
	s_and_saveexec_b64 s[4:5], s[38:39]
	s_xor_b64 s[4:5], exec, s[4:5]
	v_cvt_pk_bf16_f32 v1, v1, v2
	ds_write_b32 v218, v1 offset:7104
	s_or_b64 exec, exec, s[4:5]
	s_waitcnt lgkmcnt(0)
	v_and_b32_e32 v219, 63, v0
	v_and_b32_e32 v224, 0x1c0, v0
	v_lshlrev_b32_e32 v224, 7, v224
	v_lshl_add_u32 v224, v219, 4, v224
	ds_read_b128 v[232:235], v224
	ds_read_b128 v[236:239], v224 offset:1024
	ds_read_b128 v[240:243], v224 offset:2048
	ds_read_b128 v[244:247], v224 offset:3072
	v_lshrrev_b32_e32 v226, 4, v219
	v_lshlrev_b32_e32 v226, 12, v226
	v_and_b32_e32 v225, 15, v219
	v_lshl_add_u32 v226, v225, 4, v226
	v_and_b32_e32 v225, 31, v219
	v_lshlrev_b32_e32 v225, 1, v225
	v_sub_u32_e32 v226, v226, v225
	v_and_b32_e32 v225, 32, v219
	v_lshlrev_b32_e32 v225, 9, v225
	v_sub_u32_e32 v226, v226, v225
	v_ashrrev_i32_e32 v227, 31, v226
	v_lshl_add_u64 v[228:229], v[84:85], 0, v[226:227]
	s_mov_b64 s[4:5], 0x4000
	v_lshl_add_u64 v[230:231], v[228:229], 0, s[4:5]
	s_waitcnt lgkmcnt(3)
	global_store_dwordx4 v[228:229], v[232:235], off
	v_lshl_add_u64 v[228:229], v[230:231], 0, s[4:5]
	s_waitcnt lgkmcnt(2)
	global_store_dwordx4 v[230:231], v[236:239], off
	v_lshl_add_u64 v[230:231], v[228:229], 0, s[4:5]
	s_waitcnt lgkmcnt(1)
	global_store_dwordx4 v[228:229], v[240:243], off
	v_lshl_add_u64 v[228:229], v[230:231], 0, s[4:5]
	s_waitcnt lgkmcnt(0)
	global_store_dwordx4 v[230:231], v[244:247], off
	ds_read_b128 v[232:235], v224 offset:4096
	ds_read_b128 v[236:239], v224 offset:5120
	ds_read_b128 v[240:243], v224 offset:6144
	ds_read_b128 v[244:247], v224 offset:7168
	v_lshl_add_u64 v[230:231], v[228:229], 0, s[4:5]
	s_waitcnt lgkmcnt(3)
	global_store_dwordx4 v[228:229], v[232:235], off
	v_lshl_add_u64 v[228:229], v[230:231], 0, s[4:5]
	s_waitcnt lgkmcnt(2)
	global_store_dwordx4 v[230:231], v[236:239], off
	v_lshl_add_u64 v[230:231], v[228:229], 0, s[4:5]
	s_waitcnt lgkmcnt(1)
	global_store_dwordx4 v[228:229], v[240:243], off
	s_waitcnt lgkmcnt(0)
	global_store_dwordx4 v[230:231], v[244:247], off
	s_branch .LBB0_471

.LBB0_701:
	s_ashr_i32 s5, s9, 31
	s_add_u32 s4, s10, s9
	s_addc_u32 s5, s11, s5
	s_lshl_b64 s[4:5], s[4:5], 12
	v_readlane_b32 s9, v252, 59
	s_add_u32 s10, s9, s4
	v_readlane_b32 s4, v252, 60
	s_addc_u32 s11, s4, s5
	s_ashr_i32 s9, s8, 31
	s_lshl_b64 s[4:5], s[8:9], 1
	s_add_u32 s4, s10, s4
	s_addc_u32 s5, s11, s5
	v_lshlrev_b32_e32 v34, 1, v186
	v_and_b32_e32 v1, 1, v1
	v_lshlrev_b32_e32 v36, 14, v187
	v_lshl_add_u64 v[38:39], s[4:5], 0, v[34:35]
	v_mov_b32_e32 v37, v35
	v_cmp_eq_u32_e64 s[38:39], 0, v1
	v_lshl_add_u64 v[36:37], v[38:39], 0, v[36:37]
	v_mov_b32_dpp v1, v66 quad_perm:[1,0,3,2] row_mask:0xf bank_mask:0xf bound_ctrl:1
	v_and_b32_e32 v218, 0x1c0, v0
	v_lshlrev_b32_e32 v218, 7, v218
	v_and_b32_e32 v219, 32, v0
	v_lshl_add_u32 v218, v219, 5, v218
	v_and_b32_e32 v219, 31, v0
	v_lshl_add_u32 v218, v219, 1, v218
	s_and_saveexec_b64 s[4:5], s[38:39]
	v_cvt_pk_bf16_f32 v1, v66, v1
	ds_write_b32 v218, v1 offset:0
.LBB0_703:
	s_or_b64 exec, exec, s[4:5]
	v_mov_b32_dpp v1, v50 quad_perm:[1,0,3,2] row_mask:0xf bank_mask:0xf bound_ctrl:1
	s_and_saveexec_b64 s[4:5], s[38:39]
	v_cvt_pk_bf16_f32 v1, v50, v1
	ds_write_b32 v218, v1 offset:64
.LBB0_705:
	s_or_b64 exec, exec, s[4:5]
	v_mov_b32_dpp v1, v18 quad_perm:[1,0,3,2] row_mask:0xf bank_mask:0xf bound_ctrl:1
	s_and_saveexec_b64 s[4:5], s[38:39]
	v_cvt_pk_bf16_f32 v1, v18, v1
	ds_write_b32 v218, v1 offset:128
.LBB0_707:
	s_or_b64 exec, exec, s[4:5]
	v_mov_b32_dpp v1, v2 quad_perm:[1,0,3,2] row_mask:0xf bank_mask:0xf bound_ctrl:1
	s_and_saveexec_b64 s[4:5], s[38:39]
	v_cvt_pk_bf16_f32 v1, v2, v1
	ds_write_b32 v218, v1 offset:192
.LBB0_709:
	s_or_b64 exec, exec, s[4:5]
	v_mov_b32_dpp v1, v67 quad_perm:[1,0,3,2] row_mask:0xf bank_mask:0xf bound_ctrl:1
	s_and_saveexec_b64 s[4:5], s[38:39]
	v_cvt_pk_bf16_f32 v1, v67, v1
	ds_write_b32 v218, v1 offset:256
.LBB0_711:
	s_or_b64 exec, exec, s[4:5]
	v_mov_b32_dpp v1, v51 quad_perm:[1,0,3,2] row_mask:0xf bank_mask:0xf bound_ctrl:1
	s_and_saveexec_b64 s[4:5], s[38:39]
	v_cvt_pk_bf16_f32 v1, v51, v1
	ds_write_b32 v218, v1 offset:320
.LBB0_713:
	s_or_b64 exec, exec, s[4:5]
	v_mov_b32_dpp v1, v19 quad_perm:[1,0,3,2] row_mask:0xf bank_mask:0xf bound_ctrl:1
	s_and_saveexec_b64 s[4:5], s[38:39]
	v_cvt_pk_bf16_f32 v1, v19, v1
	ds_write_b32 v218, v1 offset:384
.LBB0_715:
	s_or_b64 exec, exec, s[4:5]
	v_mov_b32_dpp v1, v3 quad_perm:[1,0,3,2] row_mask:0xf bank_mask:0xf bound_ctrl:1
	s_and_saveexec_b64 s[4:5], s[38:39]
	v_cvt_pk_bf16_f32 v1, v3, v1
	ds_write_b32 v218, v1 offset:448
.LBB0_717:
	s_or_b64 exec, exec, s[4:5]
	v_mov_b32_dpp v1, v68 quad_perm:[1,0,3,2] row_mask:0xf bank_mask:0xf bound_ctrl:1
	s_and_saveexec_b64 s[4:5], s[38:39]
	v_cvt_pk_bf16_f32 v1, v68, v1
	ds_write_b32 v218, v1 offset:512
.LBB0_719:
	s_or_b64 exec, exec, s[4:5]
	v_mov_b32_dpp v1, v52 quad_perm:[1,0,3,2] row_mask:0xf bank_mask:0xf bound_ctrl:1
	s_and_saveexec_b64 s[4:5], s[38:39]
	v_cvt_pk_bf16_f32 v1, v52, v1
	ds_write_b32 v218, v1 offset:576
.LBB0_721:
	s_or_b64 exec, exec, s[4:5]
	v_mov_b32_dpp v1, v20 quad_perm:[1,0,3,2] row_mask:0xf bank_mask:0xf bound_ctrl:1
	s_and_saveexec_b64 s[4:5], s[38:39]
	v_cvt_pk_bf16_f32 v1, v20, v1
	ds_write_b32 v218, v1 offset:640
.LBB0_723:
	s_or_b64 exec, exec, s[4:5]
	v_mov_b32_dpp v1, v4 quad_perm:[1,0,3,2] row_mask:0xf bank_mask:0xf bound_ctrl:1
	s_and_saveexec_b64 s[4:5], s[38:39]
	v_cvt_pk_bf16_f32 v1, v4, v1
	ds_write_b32 v218, v1 offset:704
.LBB0_725:
	s_or_b64 exec, exec, s[4:5]
	v_mov_b32_dpp v1, v69 quad_perm:[1,0,3,2] row_mask:0xf bank_mask:0xf bound_ctrl:1
	s_and_saveexec_b64 s[4:5], s[38:39]
	v_cvt_pk_bf16_f32 v1, v69, v1
	ds_write_b32 v218, v1 offset:768
.LBB0_727:
	s_or_b64 exec, exec, s[4:5]
	v_mov_b32_dpp v1, v53 quad_perm:[1,0,3,2] row_mask:0xf bank_mask:0xf bound_ctrl:1
	s_and_saveexec_b64 s[4:5], s[38:39]
	v_cvt_pk_bf16_f32 v1, v53, v1
	ds_write_b32 v218, v1 offset:832
.LBB0_729:
	s_or_b64 exec, exec, s[4:5]
	v_mov_b32_dpp v1, v21 quad_perm:[1,0,3,2] row_mask:0xf bank_mask:0xf bound_ctrl:1
	s_and_saveexec_b64 s[4:5], s[38:39]
	v_cvt_pk_bf16_f32 v1, v21, v1
	ds_write_b32 v218, v1 offset:896
.LBB0_731:
	s_or_b64 exec, exec, s[4:5]
	v_mov_b32_dpp v1, v5 quad_perm:[1,0,3,2] row_mask:0xf bank_mask:0xf bound_ctrl:1
	s_and_saveexec_b64 s[4:5], s[38:39]
	v_cvt_pk_bf16_f32 v1, v5, v1
	ds_write_b32 v218, v1 offset:960
.LBB0_733:
	s_or_b64 exec, exec, s[4:5]
	v_mov_b32_dpp v1, v70 quad_perm:[1,0,3,2] row_mask:0xf bank_mask:0xf bound_ctrl:1
	s_and_saveexec_b64 s[4:5], s[38:39]
	v_cvt_pk_bf16_f32 v1, v70, v1
	ds_write_b32 v218, v1 offset:2048
.LBB0_735:
	s_or_b64 exec, exec, s[4:5]
	v_mov_b32_dpp v1, v54 quad_perm:[1,0,3,2] row_mask:0xf bank_mask:0xf bound_ctrl:1
	s_and_saveexec_b64 s[4:5], s[38:39]
	v_cvt_pk_bf16_f32 v1, v54, v1
	ds_write_b32 v218, v1 offset:2112
.LBB0_737:
	s_or_b64 exec, exec, s[4:5]
	v_mov_b32_dpp v1, v22 quad_perm:[1,0,3,2] row_mask:0xf bank_mask:0xf bound_ctrl:1
	s_and_saveexec_b64 s[4:5], s[38:39]
	v_cvt_pk_bf16_f32 v1, v22, v1
	ds_write_b32 v218, v1 offset:2176
.LBB0_739:
	s_or_b64 exec, exec, s[4:5]
	v_mov_b32_dpp v1, v6 quad_perm:[1,0,3,2] row_mask:0xf bank_mask:0xf bound_ctrl:1
	s_and_saveexec_b64 s[4:5], s[38:39]
	v_cvt_pk_bf16_f32 v1, v6, v1
	ds_write_b32 v218, v1 offset:2240
.LBB0_741:
	s_or_b64 exec, exec, s[4:5]
	v_mov_b32_dpp v1, v71 quad_perm:[1,0,3,2] row_mask:0xf bank_mask:0xf bound_ctrl:1
	s_and_saveexec_b64 s[4:5], s[38:39]
	v_cvt_pk_bf16_f32 v1, v71, v1
	ds_write_b32 v218, v1 offset:2304
.LBB0_743:
	s_or_b64 exec, exec, s[4:5]
	v_mov_b32_dpp v1, v55 quad_perm:[1,0,3,2] row_mask:0xf bank_mask:0xf bound_ctrl:1
	s_and_saveexec_b64 s[4:5], s[38:39]
	v_cvt_pk_bf16_f32 v1, v55, v1
	ds_write_b32 v218, v1 offset:2368
.LBB0_745:
	s_or_b64 exec, exec, s[4:5]
	v_mov_b32_dpp v1, v23 quad_perm:[1,0,3,2] row_mask:0xf bank_mask:0xf bound_ctrl:1
	s_and_saveexec_b64 s[4:5], s[38:39]
	v_cvt_pk_bf16_f32 v1, v23, v1
	ds_write_b32 v218, v1 offset:2432
.LBB0_747:
	s_or_b64 exec, exec, s[4:5]
	v_mov_b32_dpp v1, v7 quad_perm:[1,0,3,2] row_mask:0xf bank_mask:0xf bound_ctrl:1
	s_and_saveexec_b64 s[4:5], s[38:39]
	v_cvt_pk_bf16_f32 v1, v7, v1
	ds_write_b32 v218, v1 offset:2496
.LBB0_749:
	s_or_b64 exec, exec, s[4:5]
	v_mov_b32_dpp v1, v72 quad_perm:[1,0,3,2] row_mask:0xf bank_mask:0xf bound_ctrl:1
	s_and_saveexec_b64 s[4:5], s[38:39]
	v_cvt_pk_bf16_f32 v1, v72, v1
	ds_write_b32 v218, v1 offset:2560
.LBB0_751:
	s_or_b64 exec, exec, s[4:5]
	v_mov_b32_dpp v1, v56 quad_perm:[1,0,3,2] row_mask:0xf bank_mask:0xf bound_ctrl:1
	s_and_saveexec_b64 s[4:5], s[38:39]
	v_cvt_pk_bf16_f32 v1, v56, v1
	ds_write_b32 v218, v1 offset:2624
.LBB0_753:
	s_or_b64 exec, exec, s[4:5]
	v_mov_b32_dpp v1, v24 quad_perm:[1,0,3,2] row_mask:0xf bank_mask:0xf bound_ctrl:1
	s_and_saveexec_b64 s[4:5], s[38:39]
	v_cvt_pk_bf16_f32 v1, v24, v1
	ds_write_b32 v218, v1 offset:2688
.LBB0_755:
	s_or_b64 exec, exec, s[4:5]
	v_mov_b32_dpp v1, v8 quad_perm:[1,0,3,2] row_mask:0xf bank_mask:0xf bound_ctrl:1
	s_and_saveexec_b64 s[4:5], s[38:39]
	v_cvt_pk_bf16_f32 v1, v8, v1
	ds_write_b32 v218, v1 offset:2752
.LBB0_757:
	s_or_b64 exec, exec, s[4:5]
	v_mov_b32_dpp v1, v73 quad_perm:[1,0,3,2] row_mask:0xf bank_mask:0xf bound_ctrl:1
	s_and_saveexec_b64 s[4:5], s[38:39]
	v_cvt_pk_bf16_f32 v1, v73, v1
	ds_write_b32 v218, v1 offset:2816
.LBB0_759:
	s_or_b64 exec, exec, s[4:5]
	v_mov_b32_dpp v1, v57 quad_perm:[1,0,3,2] row_mask:0xf bank_mask:0xf bound_ctrl:1
	s_and_saveexec_b64 s[4:5], s[38:39]
	v_cvt_pk_bf16_f32 v1, v57, v1
	ds_write_b32 v218, v1 offset:2880
.LBB0_761:
	s_or_b64 exec, exec, s[4:5]
	v_mov_b32_dpp v1, v25 quad_perm:[1,0,3,2] row_mask:0xf bank_mask:0xf bound_ctrl:1
	s_and_saveexec_b64 s[4:5], s[38:39]
	v_cvt_pk_bf16_f32 v1, v25, v1
	ds_write_b32 v218, v1 offset:2944
.LBB0_763:
	s_or_b64 exec, exec, s[4:5]
	v_mov_b32_dpp v1, v9 quad_perm:[1,0,3,2] row_mask:0xf bank_mask:0xf bound_ctrl:1
	s_and_saveexec_b64 s[4:5], s[38:39]
	v_cvt_pk_bf16_f32 v1, v9, v1
	ds_write_b32 v218, v1 offset:3008
.LBB0_765:
	s_or_b64 exec, exec, s[4:5]
	v_mov_b32_dpp v1, v74 quad_perm:[1,0,3,2] row_mask:0xf bank_mask:0xf bound_ctrl:1
	s_and_saveexec_b64 s[4:5], s[38:39]
	v_cvt_pk_bf16_f32 v1, v74, v1
	ds_write_b32 v218, v1 offset:4096
.LBB0_767:
	s_or_b64 exec, exec, s[4:5]
	v_mov_b32_dpp v1, v58 quad_perm:[1,0,3,2] row_mask:0xf bank_mask:0xf bound_ctrl:1
	s_and_saveexec_b64 s[4:5], s[38:39]
	v_cvt_pk_bf16_f32 v1, v58, v1
	ds_write_b32 v218, v1 offset:4160
.LBB0_769:
	s_or_b64 exec, exec, s[4:5]
	v_mov_b32_dpp v1, v26 quad_perm:[1,0,3,2] row_mask:0xf bank_mask:0xf bound_ctrl:1
	s_and_saveexec_b64 s[4:5], s[38:39]
	v_cvt_pk_bf16_f32 v1, v26, v1
	ds_write_b32 v218, v1 offset:4224
.LBB0_771:
	s_or_b64 exec, exec, s[4:5]
	v_mov_b32_dpp v1, v10 quad_perm:[1,0,3,2] row_mask:0xf bank_mask:0xf bound_ctrl:1
	s_and_saveexec_b64 s[4:5], s[38:39]
	v_cvt_pk_bf16_f32 v1, v10, v1
	ds_write_b32 v218, v1 offset:4288
.LBB0_773:
	s_or_b64 exec, exec, s[4:5]
	v_mov_b32_dpp v1, v75 quad_perm:[1,0,3,2] row_mask:0xf bank_mask:0xf bound_ctrl:1
	s_and_saveexec_b64 s[4:5], s[38:39]
	v_cvt_pk_bf16_f32 v1, v75, v1
	ds_write_b32 v218, v1 offset:4352
.LBB0_775:
	s_or_b64 exec, exec, s[4:5]
	v_mov_b32_dpp v1, v59 quad_perm:[1,0,3,2] row_mask:0xf bank_mask:0xf bound_ctrl:1
	s_and_saveexec_b64 s[4:5], s[38:39]
	v_cvt_pk_bf16_f32 v1, v59, v1
	ds_write_b32 v218, v1 offset:4416
.LBB0_777:
	s_or_b64 exec, exec, s[4:5]
	v_mov_b32_dpp v1, v27 quad_perm:[1,0,3,2] row_mask:0xf bank_mask:0xf bound_ctrl:1
	s_and_saveexec_b64 s[4:5], s[38:39]
	v_cvt_pk_bf16_f32 v1, v27, v1
	ds_write_b32 v218, v1 offset:4480
.LBB0_779:
	s_or_b64 exec, exec, s[4:5]
	v_mov_b32_dpp v1, v11 quad_perm:[1,0,3,2] row_mask:0xf bank_mask:0xf bound_ctrl:1
	s_and_saveexec_b64 s[4:5], s[38:39]
	v_cvt_pk_bf16_f32 v1, v11, v1
	ds_write_b32 v218, v1 offset:4544
.LBB0_781:
	s_or_b64 exec, exec, s[4:5]
	v_mov_b32_dpp v1, v76 quad_perm:[1,0,3,2] row_mask:0xf bank_mask:0xf bound_ctrl:1
	s_and_saveexec_b64 s[4:5], s[38:39]
	v_cvt_pk_bf16_f32 v1, v76, v1
	ds_write_b32 v218, v1 offset:4608
.LBB0_783:
	s_or_b64 exec, exec, s[4:5]
	v_mov_b32_dpp v1, v60 quad_perm:[1,0,3,2] row_mask:0xf bank_mask:0xf bound_ctrl:1
	s_and_saveexec_b64 s[4:5], s[38:39]
	v_cvt_pk_bf16_f32 v1, v60, v1
	ds_write_b32 v218, v1 offset:4672
.LBB0_785:
	s_or_b64 exec, exec, s[4:5]
	v_mov_b32_dpp v1, v28 quad_perm:[1,0,3,2] row_mask:0xf bank_mask:0xf bound_ctrl:1
	s_and_saveexec_b64 s[4:5], s[38:39]
	v_cvt_pk_bf16_f32 v1, v28, v1
	ds_write_b32 v218, v1 offset:4736
.LBB0_787:
	s_or_b64 exec, exec, s[4:5]
	v_mov_b32_dpp v1, v12 quad_perm:[1,0,3,2] row_mask:0xf bank_mask:0xf bound_ctrl:1
	s_and_saveexec_b64 s[4:5], s[38:39]
	v_cvt_pk_bf16_f32 v1, v12, v1
	ds_write_b32 v218, v1 offset:4800
.LBB0_789:
	s_or_b64 exec, exec, s[4:5]
	v_mov_b32_dpp v1, v77 quad_perm:[1,0,3,2] row_mask:0xf bank_mask:0xf bound_ctrl:1
	s_and_saveexec_b64 s[4:5], s[38:39]
	v_cvt_pk_bf16_f32 v1, v77, v1
	ds_write_b32 v218, v1 offset:4864
.LBB0_791:
	s_or_b64 exec, exec, s[4:5]
	v_mov_b32_dpp v1, v61 quad_perm:[1,0,3,2] row_mask:0xf bank_mask:0xf bound_ctrl:1
	s_and_saveexec_b64 s[4:5], s[38:39]
	v_cvt_pk_bf16_f32 v1, v61, v1
	ds_write_b32 v218, v1 offset:4928
.LBB0_793:
	s_or_b64 exec, exec, s[4:5]
	v_mov_b32_dpp v1, v29 quad_perm:[1,0,3,2] row_mask:0xf bank_mask:0xf bound_ctrl:1
	s_and_saveexec_b64 s[4:5], s[38:39]
	v_cvt_pk_bf16_f32 v1, v29, v1
	ds_write_b32 v218, v1 offset:4992
.LBB0_795:
	s_or_b64 exec, exec, s[4:5]
	v_mov_b32_dpp v1, v13 quad_perm:[1,0,3,2] row_mask:0xf bank_mask:0xf bound_ctrl:1
	s_and_saveexec_b64 s[4:5], s[38:39]
	v_cvt_pk_bf16_f32 v1, v13, v1
	ds_write_b32 v218, v1 offset:5056
.LBB0_797:
	s_or_b64 exec, exec, s[4:5]
	v_mov_b32_dpp v1, v78 quad_perm:[1,0,3,2] row_mask:0xf bank_mask:0xf bound_ctrl:1
	s_and_saveexec_b64 s[4:5], s[38:39]
	v_cvt_pk_bf16_f32 v1, v78, v1
	ds_write_b32 v218, v1 offset:6144
.LBB0_799:
	s_or_b64 exec, exec, s[4:5]
	v_mov_b32_dpp v1, v62 quad_perm:[1,0,3,2] row_mask:0xf bank_mask:0xf bound_ctrl:1
	s_and_saveexec_b64 s[4:5], s[38:39]
	v_cvt_pk_bf16_f32 v1, v62, v1
	ds_write_b32 v218, v1 offset:6208
.LBB0_801:
	s_or_b64 exec, exec, s[4:5]
	v_mov_b32_dpp v1, v30 quad_perm:[1,0,3,2] row_mask:0xf bank_mask:0xf bound_ctrl:1
	s_and_saveexec_b64 s[4:5], s[38:39]
	v_cvt_pk_bf16_f32 v1, v30, v1
	ds_write_b32 v218, v1 offset:6272
.LBB0_803:
	s_or_b64 exec, exec, s[4:5]
	v_mov_b32_dpp v1, v14 quad_perm:[1,0,3,2] row_mask:0xf bank_mask:0xf bound_ctrl:1
	s_and_saveexec_b64 s[4:5], s[38:39]
	v_cvt_pk_bf16_f32 v1, v14, v1
	ds_write_b32 v218, v1 offset:6336
.LBB0_805:
	s_or_b64 exec, exec, s[4:5]
	v_mov_b32_dpp v1, v79 quad_perm:[1,0,3,2] row_mask:0xf bank_mask:0xf bound_ctrl:1
	s_and_saveexec_b64 s[4:5], s[38:39]
	v_cvt_pk_bf16_f32 v1, v79, v1
	ds_write_b32 v218, v1 offset:6400
.LBB0_807:
	s_or_b64 exec, exec, s[4:5]
	v_mov_b32_dpp v1, v63 quad_perm:[1,0,3,2] row_mask:0xf bank_mask:0xf bound_ctrl:1
	s_and_saveexec_b64 s[4:5], s[38:39]
	v_cvt_pk_bf16_f32 v1, v63, v1
	ds_write_b32 v218, v1 offset:6464
.LBB0_809:
	s_or_b64 exec, exec, s[4:5]
	v_mov_b32_dpp v1, v31 quad_perm:[1,0,3,2] row_mask:0xf bank_mask:0xf bound_ctrl:1
	s_and_saveexec_b64 s[4:5], s[38:39]
	v_cvt_pk_bf16_f32 v1, v31, v1
	ds_write_b32 v218, v1 offset:6528
.LBB0_811:
	s_or_b64 exec, exec, s[4:5]
	v_mov_b32_dpp v1, v15 quad_perm:[1,0,3,2] row_mask:0xf bank_mask:0xf bound_ctrl:1
	s_and_saveexec_b64 s[4:5], s[38:39]
	v_cvt_pk_bf16_f32 v1, v15, v1
	ds_write_b32 v218, v1 offset:6592
.LBB0_813:
	s_or_b64 exec, exec, s[4:5]
	v_mov_b32_dpp v1, v80 quad_perm:[1,0,3,2] row_mask:0xf bank_mask:0xf bound_ctrl:1
	s_and_saveexec_b64 s[4:5], s[38:39]
	v_cvt_pk_bf16_f32 v1, v80, v1
	ds_write_b32 v218, v1 offset:6656
.LBB0_815:
	s_or_b64 exec, exec, s[4:5]
	v_mov_b32_dpp v1, v64 quad_perm:[1,0,3,2] row_mask:0xf bank_mask:0xf bound_ctrl:1
	s_and_saveexec_b64 s[4:5], s[38:39]
	v_cvt_pk_bf16_f32 v1, v64, v1
	ds_write_b32 v218, v1 offset:6720
.LBB0_817:
	s_or_b64 exec, exec, s[4:5]
	v_mov_b32_dpp v1, v32 quad_perm:[1,0,3,2] row_mask:0xf bank_mask:0xf bound_ctrl:1
	s_and_saveexec_b64 s[4:5], s[38:39]
	v_cvt_pk_bf16_f32 v1, v32, v1
	ds_write_b32 v218, v1 offset:6784
.LBB0_819:
	s_or_b64 exec, exec, s[4:5]
	v_mov_b32_dpp v1, v16 quad_perm:[1,0,3,2] row_mask:0xf bank_mask:0xf bound_ctrl:1
	s_and_saveexec_b64 s[4:5], s[38:39]
	v_cvt_pk_bf16_f32 v1, v16, v1
	ds_write_b32 v218, v1 offset:6848
.LBB0_821:
	s_or_b64 exec, exec, s[4:5]
	v_mov_b32_dpp v1, v81 quad_perm:[1,0,3,2] row_mask:0xf bank_mask:0xf bound_ctrl:1
	s_and_saveexec_b64 s[4:5], s[38:39]
	v_cvt_pk_bf16_f32 v1, v81, v1
	ds_write_b32 v218, v1 offset:6912
.LBB0_823:
	s_or_b64 exec, exec, s[4:5]
	v_mov_b32_dpp v1, v65 quad_perm:[1,0,3,2] row_mask:0xf bank_mask:0xf bound_ctrl:1
	s_and_saveexec_b64 s[4:5], s[38:39]
	v_cvt_pk_bf16_f32 v1, v65, v1
	ds_write_b32 v218, v1 offset:6976
.LBB0_825:
	s_or_b64 exec, exec, s[4:5]
	v_mov_b32_dpp v1, v33 quad_perm:[1,0,3,2] row_mask:0xf bank_mask:0xf bound_ctrl:1
	s_and_saveexec_b64 s[4:5], s[38:39]
	v_cvt_pk_bf16_f32 v1, v33, v1
	ds_write_b32 v218, v1 offset:7040
.LBB0_827:
	s_or_b64 exec, exec, s[4:5]
	v_mov_b32_dpp v1, v17 quad_perm:[1,0,3,2] row_mask:0xf bank_mask:0xf bound_ctrl:1
	s_and_saveexec_b64 s[4:5], s[38:39]
	v_cvt_pk_bf16_f32 v1, v17, v1
	ds_write_b32 v218, v1 offset:7104
	s_or_b64 exec, exec, s[4:5]
	s_waitcnt lgkmcnt(0)
	v_and_b32_e32 v219, 63, v0
	v_and_b32_e32 v224, 0x1c0, v0
	v_lshlrev_b32_e32 v224, 7, v224
	v_lshl_add_u32 v224, v219, 4, v224
	ds_read_b128 v[232:235], v224
	ds_read_b128 v[236:239], v224 offset:1024
	ds_read_b128 v[240:243], v224 offset:2048
	ds_read_b128 v[244:247], v224 offset:3072
	v_lshrrev_b32_e32 v226, 4, v219
	v_lshlrev_b32_e32 v226, 12, v226
	v_and_b32_e32 v225, 15, v219
	v_lshl_add_u32 v226, v225, 4, v226
	v_and_b32_e32 v225, 31, v219
	v_lshlrev_b32_e32 v225, 1, v225
	v_sub_u32_e32 v226, v226, v225
	v_and_b32_e32 v225, 32, v219
	v_lshlrev_b32_e32 v225, 9, v225
	v_sub_u32_e32 v226, v226, v225
	v_ashrrev_i32_e32 v227, 31, v226
	v_lshl_add_u64 v[228:229], v[36:37], 0, v[226:227]
	s_mov_b64 s[4:5], 0x4000
	v_lshl_add_u64 v[230:231], v[228:229], 0, s[4:5]
	s_waitcnt lgkmcnt(3)
	global_store_dwordx4 v[228:229], v[232:235], off
	v_lshl_add_u64 v[228:229], v[230:231], 0, s[4:5]
	s_waitcnt lgkmcnt(2)
	global_store_dwordx4 v[230:231], v[236:239], off
	v_lshl_add_u64 v[230:231], v[228:229], 0, s[4:5]
	s_waitcnt lgkmcnt(1)
	global_store_dwordx4 v[228:229], v[240:243], off
	v_lshl_add_u64 v[228:229], v[230:231], 0, s[4:5]
	s_waitcnt lgkmcnt(0)
	global_store_dwordx4 v[230:231], v[244:247], off
	ds_read_b128 v[232:235], v224 offset:4096
	ds_read_b128 v[236:239], v224 offset:5120
	ds_read_b128 v[240:243], v224 offset:6144
	ds_read_b128 v[244:247], v224 offset:7168
	v_lshl_add_u64 v[230:231], v[228:229], 0, s[4:5]
	s_waitcnt lgkmcnt(3)
	global_store_dwordx4 v[228:229], v[232:235], off
	v_lshl_add_u64 v[228:229], v[230:231], 0, s[4:5]
	s_waitcnt lgkmcnt(2)
	global_store_dwordx4 v[230:231], v[236:239], off
	v_lshl_add_u64 v[230:231], v[228:229], 0, s[4:5]
	s_waitcnt lgkmcnt(1)
	global_store_dwordx4 v[228:229], v[240:243], off
	s_waitcnt lgkmcnt(0)
	global_store_dwordx4 v[230:231], v[244:247], off
	s_branch .LBB0_650
